# FFN-up epilogues: removed 156 s_nop pads before DPP conv groups where no operand was written in the two preceding slots (on top of plain epilogue stores + attention counted waits)
# baseline (speedup 1.0000x reference)
.LBB0_390:
	s_or_b64 exec, exec, s[8:9]
	s_waitcnt lgkmcnt(0)
	s_barrier
	v_add_u32_e32 v187, s5, v189
	ds_read_b128 v[148:151], v187 offset:9216
	ds_read_b128 v[152:155], v187 offset:8192
	ds_read_b128 v[40:43], v187 offset:10240
	ds_read_b128 v[160:163], v187 offset:11264
	s_add_i32 s4, s5, s81
	s_add_i32 s12, s4, 0xfffffc00
	v_cmp_eq_u32_e64 s[8:9], 0, v210
	v_cmp_gt_u32_e64 s[10:11], 2, v210
	s_waitcnt lgkmcnt(0)
	v_pk_fma_f32 v[6:7], v[166:167], v[42:43], v[162:163]
	v_pk_fma_f32 v[4:5], v[164:165], v[40:41], v[160:161]
	v_add_u32_e32 v191, s12, v189
	s_add_i32 s12, s4, 0xfffff800
	v_fmac_f32_dpp v4, v164, v148 row_shr:1 row_mask:0xf bank_mask:0xf bound_ctrl:1
	v_fmac_f32_dpp v5, v165, v149 row_shr:1 row_mask:0xf bank_mask:0xf bound_ctrl:1
	v_fmac_f32_dpp v4, v164, v152 row_shr:2 row_mask:0xf bank_mask:0xf bound_ctrl:1
	v_fmac_f32_dpp v5, v165, v153 row_shr:2 row_mask:0xf bank_mask:0xf bound_ctrl:1
	v_fmac_f32_dpp v6, v166, v150 row_shr:1 row_mask:0xf bank_mask:0xf bound_ctrl:1
	v_fmac_f32_dpp v7, v167, v151 row_shr:1 row_mask:0xf bank_mask:0xf bound_ctrl:1
	v_fmac_f32_dpp v6, v166, v154 row_shr:2 row_mask:0xf bank_mask:0xf bound_ctrl:1
	v_fmac_f32_dpp v7, v167, v155 row_shr:2 row_mask:0xf bank_mask:0xf bound_ctrl:1
	v_cndmask_b32_e64 v195, 0, v148, s[8:9]
	v_cndmask_b32_e64 v211, 0, v152, s[10:11]
	v_cndmask_b32_e64 v201, 0, v149, s[8:9]
	v_cndmask_b32_e64 v213, 0, v153, s[10:11]
	v_cndmask_b32_e64 v199, 0, v150, s[8:9]
	v_cndmask_b32_e64 v212, 0, v154, s[10:11]
	v_cndmask_b32_e64 v197, 0, v151, s[8:9]
	v_cndmask_b32_e64 v210, 0, v155, s[10:11]
	v_add_u32_e32 v193, s12, v189
	v_fmac_f32_dpp v4, v156, v195 row_ror:1 row_mask:0xf bank_mask:0xf
	v_fmac_f32_dpp v5, v157, v201 row_ror:1 row_mask:0xf bank_mask:0xf
	v_fmac_f32_dpp v4, v156, v211 row_ror:2 row_mask:0xf bank_mask:0xf
	v_fmac_f32_dpp v5, v157, v213 row_ror:2 row_mask:0xf bank_mask:0xf
	v_fmac_f32_dpp v6, v158, v199 row_ror:1 row_mask:0xf bank_mask:0xf
	v_fmac_f32_dpp v7, v159, v197 row_ror:1 row_mask:0xf bank_mask:0xf
	v_fmac_f32_dpp v6, v158, v212 row_ror:2 row_mask:0xf bank_mask:0xf
	v_fmac_f32_dpp v7, v159, v210 row_ror:2 row_mask:0xf bank_mask:0xf
	s_nop 0
	v_pk_fma_f32 v[18:19], v[158:159], v[42:43], v[162:163]
	v_pk_fma_f32 v[16:17], v[156:157], v[40:41], v[160:161]
	v_mov_b32_e32 v1, v19
	v_mov_b32_e32 v0, v17
	s_nop 1
	v_fmac_f32_dpp v16, v156, v148 row_shr:1 row_mask:0xf bank_mask:0xf bound_ctrl:1
	v_fmac_f32_dpp v0, v157, v149 row_shr:1 row_mask:0xf bank_mask:0xf bound_ctrl:1
	v_fmac_f32_dpp v16, v156, v152 row_shr:2 row_mask:0xf bank_mask:0xf bound_ctrl:1
	v_fmac_f32_dpp v0, v157, v153 row_shr:2 row_mask:0xf bank_mask:0xf bound_ctrl:1
	v_fmac_f32_dpp v18, v158, v150 row_shr:1 row_mask:0xf bank_mask:0xf bound_ctrl:1
	v_fmac_f32_dpp v1, v159, v151 row_shr:1 row_mask:0xf bank_mask:0xf bound_ctrl:1
	v_fmac_f32_dpp v18, v158, v154 row_shr:2 row_mask:0xf bank_mask:0xf bound_ctrl:1
	v_fmac_f32_dpp v1, v159, v155 row_shr:2 row_mask:0xf bank_mask:0xf bound_ctrl:1
	s_nop 0
	v_fmac_f32_dpp v16, v144, v195 row_ror:1 row_mask:0xf bank_mask:0xf
	v_fmac_f32_dpp v0, v145, v201 row_ror:1 row_mask:0xf bank_mask:0xf
	v_fmac_f32_dpp v16, v144, v211 row_ror:2 row_mask:0xf bank_mask:0xf
	v_fmac_f32_dpp v0, v145, v213 row_ror:2 row_mask:0xf bank_mask:0xf
	v_fmac_f32_dpp v18, v146, v199 row_ror:1 row_mask:0xf bank_mask:0xf
	v_fmac_f32_dpp v1, v147, v197 row_ror:1 row_mask:0xf bank_mask:0xf
	v_fmac_f32_dpp v18, v146, v212 row_ror:2 row_mask:0xf bank_mask:0xf
	v_fmac_f32_dpp v1, v147, v210 row_ror:2 row_mask:0xf bank_mask:0xf
	s_nop 0
	v_mov_b32_e32 v17, v0
	v_mov_b32_e32 v19, v1
	v_pk_fma_f32 v[34:35], v[146:147], v[42:43], v[162:163]
	v_pk_fma_f32 v[32:33], v[144:145], v[40:41], v[160:161]
	v_mov_b32_e32 v0, v35
	s_nop 1
	v_fmac_f32_dpp v32, v144, v148 row_shr:1 row_mask:0xf bank_mask:0xf bound_ctrl:1
	v_fmac_f32_dpp v33, v145, v149 row_shr:1 row_mask:0xf bank_mask:0xf bound_ctrl:1
	v_fmac_f32_dpp v32, v144, v152 row_shr:2 row_mask:0xf bank_mask:0xf bound_ctrl:1
	v_fmac_f32_dpp v33, v145, v153 row_shr:2 row_mask:0xf bank_mask:0xf bound_ctrl:1
	v_fmac_f32_dpp v34, v146, v150 row_shr:1 row_mask:0xf bank_mask:0xf bound_ctrl:1
	v_fmac_f32_dpp v0, v147, v151 row_shr:1 row_mask:0xf bank_mask:0xf bound_ctrl:1
	v_fmac_f32_dpp v34, v146, v154 row_shr:2 row_mask:0xf bank_mask:0xf bound_ctrl:1
	v_fmac_f32_dpp v0, v147, v155 row_shr:2 row_mask:0xf bank_mask:0xf bound_ctrl:1
	s_nop 0
	v_fmac_f32_dpp v32, v140, v195 row_ror:1 row_mask:0xf bank_mask:0xf
	v_fmac_f32_dpp v33, v141, v201 row_ror:1 row_mask:0xf bank_mask:0xf
	v_fmac_f32_dpp v32, v140, v211 row_ror:2 row_mask:0xf bank_mask:0xf
	v_fmac_f32_dpp v33, v141, v213 row_ror:2 row_mask:0xf bank_mask:0xf
	v_fmac_f32_dpp v34, v142, v199 row_ror:1 row_mask:0xf bank_mask:0xf
	v_fmac_f32_dpp v0, v143, v197 row_ror:1 row_mask:0xf bank_mask:0xf
	v_fmac_f32_dpp v34, v142, v212 row_ror:2 row_mask:0xf bank_mask:0xf
	v_fmac_f32_dpp v0, v143, v210 row_ror:2 row_mask:0xf bank_mask:0xf
	s_nop 0
	v_mov_b32_e32 v35, v0
	v_pk_fma_f32 v[0:1], v[142:143], v[42:43], v[162:163]
	v_pk_fma_f32 v[2:3], v[140:141], v[40:41], v[160:161]
	v_mov_b32_e32 v62, v0
	v_mov_b32_e32 v60, v2
	v_cndmask_b32_e64 v0, 0, 1, s[36:37]
	s_nop 1
	v_fmac_f32_dpp v60, v140, v148 row_shr:1 row_mask:0xf bank_mask:0xf bound_ctrl:1
	v_fmac_f32_dpp v3, v141, v149 row_shr:1 row_mask:0xf bank_mask:0xf bound_ctrl:1
	v_fmac_f32_dpp v60, v140, v152 row_shr:2 row_mask:0xf bank_mask:0xf bound_ctrl:1
	v_fmac_f32_dpp v3, v141, v153 row_shr:2 row_mask:0xf bank_mask:0xf bound_ctrl:1
	v_fmac_f32_dpp v62, v142, v150 row_shr:1 row_mask:0xf bank_mask:0xf bound_ctrl:1
	v_fmac_f32_dpp v1, v143, v151 row_shr:1 row_mask:0xf bank_mask:0xf bound_ctrl:1
	v_fmac_f32_dpp v62, v142, v154 row_shr:2 row_mask:0xf bank_mask:0xf bound_ctrl:1
	v_fmac_f32_dpp v1, v143, v155 row_shr:2 row_mask:0xf bank_mask:0xf bound_ctrl:1
	v_cmp_ne_u32_e64 s[12:13], 1, v0
	v_mov_b32_e32 v61, v3
	s_andn2_b64 vcc, exec, s[36:37]
	v_mov_b32_e32 v63, v1
	s_cbranch_vccnz .LBB0_392
	ds_read_b128 v[8:11], v191
	ds_read_b128 v[140:143], v193
	s_waitcnt lgkmcnt(0)
	v_cndmask_b32_e64 v0, v8, v140, s[8:9]
	v_mul_f32_e32 v0, v211, v0
	v_fmac_f32_e32 v0, v195, v8
	v_add_f32_e32 v60, v60, v0
	v_cndmask_b32_e64 v0, v10, v142, s[8:9]
	v_mul_f32_e32 v0, v212, v0
	v_fmac_f32_e32 v0, v199, v10
	v_cndmask_b32_e64 v2, v9, v141, s[8:9]
	v_add_f32_e32 v62, v62, v0
	v_cndmask_b32_e64 v0, v11, v143, s[8:9]
	v_mul_f32_e32 v2, v213, v2
	v_mul_f32_e32 v0, v210, v0
	v_fmac_f32_e32 v2, v201, v9
	v_fmac_f32_e32 v0, v197, v11
	v_add_f32_e32 v61, v3, v2
	v_add_f32_e32 v63, v1, v0
.LBB0_392:
	s_add_i32 s5, s5, s82
	s_add_i32 s14, s5, 0xfffffc00
	v_pk_fma_f32 v[2:3], v[22:23], v[42:43], v[162:163]
	v_pk_fma_f32 v[0:1], v[20:21], v[40:41], v[160:161]
	v_add_u32_e32 v156, s14, v189
	s_add_i32 s14, s5, 0xfffff800
	v_fmac_f32_dpp v0, v20, v148 row_shr:1 row_mask:0xf bank_mask:0xf bound_ctrl:1
	v_fmac_f32_dpp v1, v21, v149 row_shr:1 row_mask:0xf bank_mask:0xf bound_ctrl:1
	v_fmac_f32_dpp v0, v20, v152 row_shr:2 row_mask:0xf bank_mask:0xf bound_ctrl:1
	v_fmac_f32_dpp v1, v21, v153 row_shr:2 row_mask:0xf bank_mask:0xf bound_ctrl:1
	v_fmac_f32_dpp v2, v22, v150 row_shr:1 row_mask:0xf bank_mask:0xf bound_ctrl:1
	v_fmac_f32_dpp v3, v23, v151 row_shr:1 row_mask:0xf bank_mask:0xf bound_ctrl:1
	v_fmac_f32_dpp v2, v22, v154 row_shr:2 row_mask:0xf bank_mask:0xf bound_ctrl:1
	v_fmac_f32_dpp v3, v23, v155 row_shr:2 row_mask:0xf bank_mask:0xf bound_ctrl:1
	v_add_u32_e32 v157, s14, v189
	v_fmac_f32_dpp v0, v48, v195 row_ror:1 row_mask:0xf bank_mask:0xf
	v_fmac_f32_dpp v1, v49, v201 row_ror:1 row_mask:0xf bank_mask:0xf
	v_fmac_f32_dpp v0, v48, v211 row_ror:2 row_mask:0xf bank_mask:0xf
	v_fmac_f32_dpp v1, v49, v213 row_ror:2 row_mask:0xf bank_mask:0xf
	v_fmac_f32_dpp v2, v50, v199 row_ror:1 row_mask:0xf bank_mask:0xf
	v_fmac_f32_dpp v3, v51, v197 row_ror:1 row_mask:0xf bank_mask:0xf
	v_fmac_f32_dpp v2, v50, v212 row_ror:2 row_mask:0xf bank_mask:0xf
	v_fmac_f32_dpp v3, v51, v210 row_ror:2 row_mask:0xf bank_mask:0xf
	s_nop 0
	v_pk_fma_f32 v[10:11], v[50:51], v[42:43], v[162:163]
	v_pk_fma_f32 v[8:9], v[48:49], v[40:41], v[160:161]
	s_nop 0
	s_nop 1
	v_fmac_f32_dpp v8, v48, v148 row_shr:1 row_mask:0xf bank_mask:0xf bound_ctrl:1
	v_fmac_f32_dpp v9, v49, v149 row_shr:1 row_mask:0xf bank_mask:0xf bound_ctrl:1
	v_fmac_f32_dpp v8, v48, v152 row_shr:2 row_mask:0xf bank_mask:0xf bound_ctrl:1
	v_fmac_f32_dpp v9, v49, v153 row_shr:2 row_mask:0xf bank_mask:0xf bound_ctrl:1
	v_fmac_f32_dpp v10, v50, v150 row_shr:1 row_mask:0xf bank_mask:0xf bound_ctrl:1
	v_fmac_f32_dpp v11, v51, v151 row_shr:1 row_mask:0xf bank_mask:0xf bound_ctrl:1
	v_fmac_f32_dpp v10, v50, v154 row_shr:2 row_mask:0xf bank_mask:0xf bound_ctrl:1
	v_fmac_f32_dpp v11, v51, v155 row_shr:2 row_mask:0xf bank_mask:0xf bound_ctrl:1
	s_nop 0
	v_fmac_f32_dpp v8, v68, v195 row_ror:1 row_mask:0xf bank_mask:0xf
	v_fmac_f32_dpp v9, v69, v201 row_ror:1 row_mask:0xf bank_mask:0xf
	v_fmac_f32_dpp v8, v68, v211 row_ror:2 row_mask:0xf bank_mask:0xf
	v_fmac_f32_dpp v9, v69, v213 row_ror:2 row_mask:0xf bank_mask:0xf
	v_fmac_f32_dpp v10, v70, v199 row_ror:1 row_mask:0xf bank_mask:0xf
	v_fmac_f32_dpp v11, v71, v197 row_ror:1 row_mask:0xf bank_mask:0xf
	v_fmac_f32_dpp v10, v70, v212 row_ror:2 row_mask:0xf bank_mask:0xf
	v_fmac_f32_dpp v11, v71, v210 row_ror:2 row_mask:0xf bank_mask:0xf
	s_nop 0
	v_pk_fma_f32 v[22:23], v[70:71], v[42:43], v[162:163]
	v_pk_fma_f32 v[20:21], v[68:69], v[40:41], v[160:161]
	s_nop 0
	s_nop 1
	v_fmac_f32_dpp v20, v68, v148 row_shr:1 row_mask:0xf bank_mask:0xf bound_ctrl:1
	v_fmac_f32_dpp v21, v69, v149 row_shr:1 row_mask:0xf bank_mask:0xf bound_ctrl:1
	v_fmac_f32_dpp v20, v68, v152 row_shr:2 row_mask:0xf bank_mask:0xf bound_ctrl:1
	v_fmac_f32_dpp v21, v69, v153 row_shr:2 row_mask:0xf bank_mask:0xf bound_ctrl:1
	v_fmac_f32_dpp v22, v70, v150 row_shr:1 row_mask:0xf bank_mask:0xf bound_ctrl:1
	v_fmac_f32_dpp v23, v71, v151 row_shr:1 row_mask:0xf bank_mask:0xf bound_ctrl:1
	v_fmac_f32_dpp v22, v70, v154 row_shr:2 row_mask:0xf bank_mask:0xf bound_ctrl:1
	v_fmac_f32_dpp v23, v71, v155 row_shr:2 row_mask:0xf bank_mask:0xf bound_ctrl:1
	s_nop 0
	v_fmac_f32_dpp v20, v80, v195 row_ror:1 row_mask:0xf bank_mask:0xf
	v_fmac_f32_dpp v21, v81, v201 row_ror:1 row_mask:0xf bank_mask:0xf
	v_fmac_f32_dpp v20, v80, v211 row_ror:2 row_mask:0xf bank_mask:0xf
	v_fmac_f32_dpp v21, v81, v213 row_ror:2 row_mask:0xf bank_mask:0xf
	v_fmac_f32_dpp v22, v82, v199 row_ror:1 row_mask:0xf bank_mask:0xf
	v_fmac_f32_dpp v23, v83, v197 row_ror:1 row_mask:0xf bank_mask:0xf
	v_fmac_f32_dpp v22, v82, v212 row_ror:2 row_mask:0xf bank_mask:0xf
	v_fmac_f32_dpp v23, v83, v210 row_ror:2 row_mask:0xf bank_mask:0xf
	s_nop 0
	v_cndmask_b32_e64 v48, 0, 1, s[38:39]
	v_pk_fma_f32 v[42:43], v[82:83], v[42:43], v[162:163]
	v_pk_fma_f32 v[40:41], v[80:81], v[40:41], v[160:161]
	v_cmp_ne_u32_e64 s[14:15], 1, v48
	s_andn2_b64 vcc, exec, s[38:39]
	s_nop 1
	v_fmac_f32_dpp v40, v80, v148 row_shr:1 row_mask:0xf bank_mask:0xf bound_ctrl:1
	v_fmac_f32_dpp v41, v81, v149 row_shr:1 row_mask:0xf bank_mask:0xf bound_ctrl:1
	v_fmac_f32_dpp v40, v80, v152 row_shr:2 row_mask:0xf bank_mask:0xf bound_ctrl:1
	v_fmac_f32_dpp v41, v81, v153 row_shr:2 row_mask:0xf bank_mask:0xf bound_ctrl:1
	v_fmac_f32_dpp v42, v82, v150 row_shr:1 row_mask:0xf bank_mask:0xf bound_ctrl:1
	v_fmac_f32_dpp v43, v83, v151 row_shr:1 row_mask:0xf bank_mask:0xf bound_ctrl:1
	v_fmac_f32_dpp v42, v82, v154 row_shr:2 row_mask:0xf bank_mask:0xf bound_ctrl:1
	v_fmac_f32_dpp v43, v83, v155 row_shr:2 row_mask:0xf bank_mask:0xf bound_ctrl:1
	s_cbranch_vccnz .LBB0_394
	ds_read_b128 v[48:51], v156
	ds_read_b128 v[68:71], v157
	s_waitcnt lgkmcnt(0)
	v_cndmask_b32_e64 v68, v48, v68, s[8:9]
	v_mul_f32_e32 v68, v211, v68
	v_fmac_f32_e32 v68, v195, v48
	v_cndmask_b32_e64 v48, v50, v70, s[8:9]
	v_mul_f32_e32 v48, v212, v48
	v_fmac_f32_e32 v48, v199, v50
	v_cndmask_b32_e64 v69, v49, v69, s[8:9]
	v_add_f32_e32 v42, v42, v48
	v_cndmask_b32_e64 v48, v51, v71, s[8:9]
	v_mul_f32_e32 v69, v213, v69
	v_mul_f32_e32 v48, v210, v48
	v_fmac_f32_e32 v69, v201, v49
	v_fmac_f32_e32 v48, v197, v51
	v_add_f32_e32 v40, v40, v68
	v_add_f32_e32 v41, v41, v69
	v_add_f32_e32 v43, v43, v48
.LBB0_394:
	ds_read_b128 v[140:143], v187 offset:9232
	ds_read_b128 v[144:147], v187 offset:8208
	ds_read_b128 v[148:151], v187 offset:10256
	ds_read_b128 v[152:155], v187 offset:11280
	s_waitcnt lgkmcnt(3)
	v_cndmask_b32_e64 v159, 0, v140, s[8:9]
	s_waitcnt lgkmcnt(2)
	v_cndmask_b32_e64 v163, 0, v144, s[10:11]
	v_cndmask_b32_e64 v161, 0, v141, s[8:9]
	s_waitcnt lgkmcnt(0)
	v_pk_fma_f32 v[68:69], v[96:97], v[148:149], v[152:153]
	v_pk_fma_f32 v[70:71], v[98:99], v[150:151], v[154:155]
	v_mov_b32_e32 v48, v69
	s_nop 1
	v_fmac_f32_dpp v68, v96, v140 row_shr:1 row_mask:0xf bank_mask:0xf bound_ctrl:1
	v_fmac_f32_dpp v48, v97, v141 row_shr:1 row_mask:0xf bank_mask:0xf bound_ctrl:1
	v_fmac_f32_dpp v68, v96, v144 row_shr:2 row_mask:0xf bank_mask:0xf bound_ctrl:1
	v_fmac_f32_dpp v48, v97, v145 row_shr:2 row_mask:0xf bank_mask:0xf bound_ctrl:1
	v_fmac_f32_dpp v70, v98, v142 row_shr:1 row_mask:0xf bank_mask:0xf bound_ctrl:1
	v_fmac_f32_dpp v71, v99, v143 row_shr:1 row_mask:0xf bank_mask:0xf bound_ctrl:1
	v_fmac_f32_dpp v70, v98, v146 row_shr:2 row_mask:0xf bank_mask:0xf bound_ctrl:1
	v_fmac_f32_dpp v71, v99, v147 row_shr:2 row_mask:0xf bank_mask:0xf bound_ctrl:1
	v_cndmask_b32_e64 v165, 0, v145, s[10:11]
	v_cndmask_b32_e64 v160, 0, v142, s[8:9]
	v_cndmask_b32_e64 v164, 0, v146, s[10:11]
	v_cndmask_b32_e64 v158, 0, v143, s[8:9]
	v_cndmask_b32_e64 v162, 0, v147, s[10:11]
	v_fmac_f32_dpp v68, v136, v159 row_ror:1 row_mask:0xf bank_mask:0xf
	v_fmac_f32_dpp v48, v137, v161 row_ror:1 row_mask:0xf bank_mask:0xf
	v_fmac_f32_dpp v68, v136, v163 row_ror:2 row_mask:0xf bank_mask:0xf
	v_fmac_f32_dpp v48, v137, v165 row_ror:2 row_mask:0xf bank_mask:0xf
	v_fmac_f32_dpp v70, v138, v160 row_ror:1 row_mask:0xf bank_mask:0xf
	v_fmac_f32_dpp v71, v139, v158 row_ror:1 row_mask:0xf bank_mask:0xf
	v_fmac_f32_dpp v70, v138, v164 row_ror:2 row_mask:0xf bank_mask:0xf
	v_fmac_f32_dpp v71, v139, v162 row_ror:2 row_mask:0xf bank_mask:0xf
	s_nop 0
	v_mov_b32_e32 v69, v48
	v_pk_fma_f32 v[82:83], v[138:139], v[150:151], v[154:155]
	v_pk_fma_f32 v[80:81], v[136:137], v[148:149], v[152:153]
	v_mov_b32_e32 v49, v83
	v_mov_b32_e32 v48, v81
	s_nop 1
	v_fmac_f32_dpp v80, v136, v140 row_shr:1 row_mask:0xf bank_mask:0xf bound_ctrl:1
	v_fmac_f32_dpp v48, v137, v141 row_shr:1 row_mask:0xf bank_mask:0xf bound_ctrl:1
	v_fmac_f32_dpp v80, v136, v144 row_shr:2 row_mask:0xf bank_mask:0xf bound_ctrl:1
	v_fmac_f32_dpp v48, v137, v145 row_shr:2 row_mask:0xf bank_mask:0xf bound_ctrl:1
	v_fmac_f32_dpp v82, v138, v142 row_shr:1 row_mask:0xf bank_mask:0xf bound_ctrl:1
	v_fmac_f32_dpp v49, v139, v143 row_shr:1 row_mask:0xf bank_mask:0xf bound_ctrl:1
	v_fmac_f32_dpp v82, v138, v146 row_shr:2 row_mask:0xf bank_mask:0xf bound_ctrl:1
	v_fmac_f32_dpp v49, v139, v147 row_shr:2 row_mask:0xf bank_mask:0xf bound_ctrl:1
	s_nop 0
	v_fmac_f32_dpp v80, v120, v159 row_ror:1 row_mask:0xf bank_mask:0xf
	v_fmac_f32_dpp v48, v121, v161 row_ror:1 row_mask:0xf bank_mask:0xf
	v_fmac_f32_dpp v80, v120, v163 row_ror:2 row_mask:0xf bank_mask:0xf
	v_fmac_f32_dpp v48, v121, v165 row_ror:2 row_mask:0xf bank_mask:0xf
	v_fmac_f32_dpp v82, v122, v160 row_ror:1 row_mask:0xf bank_mask:0xf
	v_fmac_f32_dpp v49, v123, v158 row_ror:1 row_mask:0xf bank_mask:0xf
	v_fmac_f32_dpp v82, v122, v164 row_ror:2 row_mask:0xf bank_mask:0xf
	v_fmac_f32_dpp v49, v123, v162 row_ror:2 row_mask:0xf bank_mask:0xf
	s_nop 0
	v_mov_b32_e32 v81, v48
	v_mov_b32_e32 v83, v49
	v_pk_fma_f32 v[98:99], v[122:123], v[150:151], v[154:155]
	v_pk_fma_f32 v[96:97], v[120:121], v[148:149], v[152:153]
	v_mov_b32_e32 v48, v99
	s_nop 1
	v_fmac_f32_dpp v96, v120, v140 row_shr:1 row_mask:0xf bank_mask:0xf bound_ctrl:1
	v_fmac_f32_dpp v97, v121, v141 row_shr:1 row_mask:0xf bank_mask:0xf bound_ctrl:1
	v_fmac_f32_dpp v96, v120, v144 row_shr:2 row_mask:0xf bank_mask:0xf bound_ctrl:1
	v_fmac_f32_dpp v97, v121, v145 row_shr:2 row_mask:0xf bank_mask:0xf bound_ctrl:1
	v_fmac_f32_dpp v98, v122, v142 row_shr:1 row_mask:0xf bank_mask:0xf bound_ctrl:1
	v_fmac_f32_dpp v48, v123, v143 row_shr:1 row_mask:0xf bank_mask:0xf bound_ctrl:1
	v_fmac_f32_dpp v98, v122, v146 row_shr:2 row_mask:0xf bank_mask:0xf bound_ctrl:1
	v_fmac_f32_dpp v48, v123, v147 row_shr:2 row_mask:0xf bank_mask:0xf bound_ctrl:1
	s_nop 0
	v_fmac_f32_dpp v96, v132, v159 row_ror:1 row_mask:0xf bank_mask:0xf
	v_fmac_f32_dpp v97, v133, v161 row_ror:1 row_mask:0xf bank_mask:0xf
	v_fmac_f32_dpp v96, v132, v163 row_ror:2 row_mask:0xf bank_mask:0xf
	v_fmac_f32_dpp v97, v133, v165 row_ror:2 row_mask:0xf bank_mask:0xf
	v_fmac_f32_dpp v98, v134, v160 row_ror:1 row_mask:0xf bank_mask:0xf
	v_fmac_f32_dpp v48, v135, v158 row_ror:1 row_mask:0xf bank_mask:0xf
	v_fmac_f32_dpp v98, v134, v164 row_ror:2 row_mask:0xf bank_mask:0xf
	v_fmac_f32_dpp v48, v135, v162 row_ror:2 row_mask:0xf bank_mask:0xf
	s_nop 0
	v_mov_b32_e32 v99, v48
	v_pk_fma_f32 v[48:49], v[134:135], v[150:151], v[154:155]
	v_pk_fma_f32 v[50:51], v[132:133], v[148:149], v[152:153]
	v_mov_b32_e32 v122, v48
	v_mov_b32_e32 v120, v50
	s_nop 1
	v_fmac_f32_dpp v120, v132, v140 row_shr:1 row_mask:0xf bank_mask:0xf bound_ctrl:1
	v_fmac_f32_dpp v51, v133, v141 row_shr:1 row_mask:0xf bank_mask:0xf bound_ctrl:1
	v_fmac_f32_dpp v120, v132, v144 row_shr:2 row_mask:0xf bank_mask:0xf bound_ctrl:1
	v_fmac_f32_dpp v51, v133, v145 row_shr:2 row_mask:0xf bank_mask:0xf bound_ctrl:1
	v_fmac_f32_dpp v122, v134, v142 row_shr:1 row_mask:0xf bank_mask:0xf bound_ctrl:1
	v_fmac_f32_dpp v49, v135, v143 row_shr:1 row_mask:0xf bank_mask:0xf bound_ctrl:1
	v_fmac_f32_dpp v122, v134, v146 row_shr:2 row_mask:0xf bank_mask:0xf bound_ctrl:1
	v_fmac_f32_dpp v49, v135, v147 row_shr:2 row_mask:0xf bank_mask:0xf bound_ctrl:1
	s_and_b64 vcc, exec, s[12:13]
	v_mov_b32_e32 v121, v51
	v_mov_b32_e32 v123, v49
	s_cbranch_vccnz .LBB0_396
	ds_read_b128 v[132:135], v191 offset:16
	ds_read_b128 v[136:139], v193 offset:16
	s_waitcnt lgkmcnt(0)
	v_cndmask_b32_e64 v48, v132, v136, s[8:9]
	v_mul_f32_e32 v48, v163, v48
	v_fmac_f32_e32 v48, v159, v132
	v_add_f32_e32 v120, v120, v48
	v_cndmask_b32_e64 v48, v134, v138, s[8:9]
	v_mul_f32_e32 v48, v164, v48
	v_fmac_f32_e32 v48, v160, v134
	v_cndmask_b32_e64 v50, v133, v137, s[8:9]
	v_add_f32_e32 v122, v122, v48
	v_cndmask_b32_e64 v48, v135, v139, s[8:9]
	v_mul_f32_e32 v50, v165, v50
	v_mul_f32_e32 v48, v162, v48
	v_fmac_f32_e32 v50, v161, v133
	v_fmac_f32_e32 v48, v158, v135
	v_add_f32_e32 v121, v51, v50
	v_add_f32_e32 v123, v49, v48
.LBB0_396:
	v_pk_fma_f32 v[50:51], v[74:75], v[150:151], v[154:155]
	v_pk_fma_f32 v[48:49], v[72:73], v[148:149], v[152:153]
	s_nop 0
	s_nop 1
	v_fmac_f32_dpp v48, v72, v140 row_shr:1 row_mask:0xf bank_mask:0xf bound_ctrl:1
	v_fmac_f32_dpp v49, v73, v141 row_shr:1 row_mask:0xf bank_mask:0xf bound_ctrl:1
	v_fmac_f32_dpp v48, v72, v144 row_shr:2 row_mask:0xf bank_mask:0xf bound_ctrl:1
	v_fmac_f32_dpp v49, v73, v145 row_shr:2 row_mask:0xf bank_mask:0xf bound_ctrl:1
	v_fmac_f32_dpp v50, v74, v142 row_shr:1 row_mask:0xf bank_mask:0xf bound_ctrl:1
	v_fmac_f32_dpp v51, v75, v143 row_shr:1 row_mask:0xf bank_mask:0xf bound_ctrl:1
	v_fmac_f32_dpp v50, v74, v146 row_shr:2 row_mask:0xf bank_mask:0xf bound_ctrl:1
	v_fmac_f32_dpp v51, v75, v147 row_shr:2 row_mask:0xf bank_mask:0xf bound_ctrl:1
	s_nop 0
	v_fmac_f32_dpp v48, v84, v159 row_ror:1 row_mask:0xf bank_mask:0xf
	v_fmac_f32_dpp v49, v85, v161 row_ror:1 row_mask:0xf bank_mask:0xf
	v_fmac_f32_dpp v48, v84, v163 row_ror:2 row_mask:0xf bank_mask:0xf
	v_fmac_f32_dpp v49, v85, v165 row_ror:2 row_mask:0xf bank_mask:0xf
	v_fmac_f32_dpp v50, v86, v160 row_ror:1 row_mask:0xf bank_mask:0xf
	v_fmac_f32_dpp v51, v87, v158 row_ror:1 row_mask:0xf bank_mask:0xf
	v_fmac_f32_dpp v50, v86, v164 row_ror:2 row_mask:0xf bank_mask:0xf
	v_fmac_f32_dpp v51, v87, v162 row_ror:2 row_mask:0xf bank_mask:0xf
	s_nop 0
	v_pk_fma_f32 v[74:75], v[86:87], v[150:151], v[154:155]
	v_pk_fma_f32 v[72:73], v[84:85], v[148:149], v[152:153]
	s_nop 0
	s_nop 1
	v_fmac_f32_dpp v72, v84, v140 row_shr:1 row_mask:0xf bank_mask:0xf bound_ctrl:1
	v_fmac_f32_dpp v73, v85, v141 row_shr:1 row_mask:0xf bank_mask:0xf bound_ctrl:1
	v_fmac_f32_dpp v72, v84, v144 row_shr:2 row_mask:0xf bank_mask:0xf bound_ctrl:1
	v_fmac_f32_dpp v73, v85, v145 row_shr:2 row_mask:0xf bank_mask:0xf bound_ctrl:1
	v_fmac_f32_dpp v74, v86, v142 row_shr:1 row_mask:0xf bank_mask:0xf bound_ctrl:1
	v_fmac_f32_dpp v75, v87, v143 row_shr:1 row_mask:0xf bank_mask:0xf bound_ctrl:1
	v_fmac_f32_dpp v74, v86, v146 row_shr:2 row_mask:0xf bank_mask:0xf bound_ctrl:1
	v_fmac_f32_dpp v75, v87, v147 row_shr:2 row_mask:0xf bank_mask:0xf bound_ctrl:1
	s_nop 0
	v_fmac_f32_dpp v72, v108, v159 row_ror:1 row_mask:0xf bank_mask:0xf
	v_fmac_f32_dpp v73, v109, v161 row_ror:1 row_mask:0xf bank_mask:0xf
	v_fmac_f32_dpp v72, v108, v163 row_ror:2 row_mask:0xf bank_mask:0xf
	v_fmac_f32_dpp v73, v109, v165 row_ror:2 row_mask:0xf bank_mask:0xf
	v_fmac_f32_dpp v74, v110, v160 row_ror:1 row_mask:0xf bank_mask:0xf
	v_fmac_f32_dpp v75, v111, v158 row_ror:1 row_mask:0xf bank_mask:0xf
	v_fmac_f32_dpp v74, v110, v164 row_ror:2 row_mask:0xf bank_mask:0xf
	v_fmac_f32_dpp v75, v111, v162 row_ror:2 row_mask:0xf bank_mask:0xf
	s_nop 0
	v_pk_fma_f32 v[86:87], v[110:111], v[150:151], v[154:155]
	v_pk_fma_f32 v[84:85], v[108:109], v[148:149], v[152:153]
	s_nop 0
	s_nop 1
	v_fmac_f32_dpp v84, v108, v140 row_shr:1 row_mask:0xf bank_mask:0xf bound_ctrl:1
	v_fmac_f32_dpp v85, v109, v141 row_shr:1 row_mask:0xf bank_mask:0xf bound_ctrl:1
	v_fmac_f32_dpp v84, v108, v144 row_shr:2 row_mask:0xf bank_mask:0xf bound_ctrl:1
	v_fmac_f32_dpp v85, v109, v145 row_shr:2 row_mask:0xf bank_mask:0xf bound_ctrl:1
	v_fmac_f32_dpp v86, v110, v142 row_shr:1 row_mask:0xf bank_mask:0xf bound_ctrl:1
	v_fmac_f32_dpp v87, v111, v143 row_shr:1 row_mask:0xf bank_mask:0xf bound_ctrl:1
	v_fmac_f32_dpp v86, v110, v146 row_shr:2 row_mask:0xf bank_mask:0xf bound_ctrl:1
	v_fmac_f32_dpp v87, v111, v147 row_shr:2 row_mask:0xf bank_mask:0xf bound_ctrl:1
	s_nop 0
	v_fmac_f32_dpp v84, v128, v159 row_ror:1 row_mask:0xf bank_mask:0xf
	v_fmac_f32_dpp v85, v129, v161 row_ror:1 row_mask:0xf bank_mask:0xf
	v_fmac_f32_dpp v84, v128, v163 row_ror:2 row_mask:0xf bank_mask:0xf
	v_fmac_f32_dpp v85, v129, v165 row_ror:2 row_mask:0xf bank_mask:0xf
	v_fmac_f32_dpp v86, v130, v160 row_ror:1 row_mask:0xf bank_mask:0xf
	v_fmac_f32_dpp v87, v131, v158 row_ror:1 row_mask:0xf bank_mask:0xf
	v_fmac_f32_dpp v86, v130, v164 row_ror:2 row_mask:0xf bank_mask:0xf
	v_fmac_f32_dpp v87, v131, v162 row_ror:2 row_mask:0xf bank_mask:0xf
	s_nop 0
	v_pk_fma_f32 v[110:111], v[130:131], v[150:151], v[154:155]
	v_pk_fma_f32 v[108:109], v[128:129], v[148:149], v[152:153]
	s_and_b64 vcc, exec, s[14:15]
	s_nop 1
	v_fmac_f32_dpp v108, v128, v140 row_shr:1 row_mask:0xf bank_mask:0xf bound_ctrl:1
	v_fmac_f32_dpp v109, v129, v141 row_shr:1 row_mask:0xf bank_mask:0xf bound_ctrl:1
	v_fmac_f32_dpp v108, v128, v144 row_shr:2 row_mask:0xf bank_mask:0xf bound_ctrl:1
	v_fmac_f32_dpp v109, v129, v145 row_shr:2 row_mask:0xf bank_mask:0xf bound_ctrl:1
	v_fmac_f32_dpp v110, v130, v142 row_shr:1 row_mask:0xf bank_mask:0xf bound_ctrl:1
	v_fmac_f32_dpp v111, v131, v143 row_shr:1 row_mask:0xf bank_mask:0xf bound_ctrl:1
	v_fmac_f32_dpp v110, v130, v146 row_shr:2 row_mask:0xf bank_mask:0xf bound_ctrl:1
	v_fmac_f32_dpp v111, v131, v147 row_shr:2 row_mask:0xf bank_mask:0xf bound_ctrl:1
	s_cbranch_vccnz .LBB0_398
	ds_read_b128 v[128:131], v156 offset:16
	ds_read_b128 v[132:135], v157 offset:16
	s_waitcnt lgkmcnt(0)
	v_cndmask_b32_e64 v132, v128, v132, s[8:9]
	v_mul_f32_e32 v132, v163, v132
	v_fmac_f32_e32 v132, v159, v128
	v_cndmask_b32_e64 v128, v130, v134, s[8:9]
	v_mul_f32_e32 v128, v164, v128
	v_fmac_f32_e32 v128, v160, v130
	v_cndmask_b32_e64 v133, v129, v133, s[8:9]
	v_add_f32_e32 v110, v110, v128
	v_cndmask_b32_e64 v128, v131, v135, s[8:9]
	v_mul_f32_e32 v133, v165, v133
	v_mul_f32_e32 v128, v162, v128
	v_fmac_f32_e32 v133, v161, v129
	v_fmac_f32_e32 v128, v158, v131
	v_add_f32_e32 v108, v108, v132
	v_add_f32_e32 v109, v109, v133
	v_add_f32_e32 v111, v111, v128
.LBB0_398:
	ds_read_b128 v[136:139], v187 offset:9728
	ds_read_b128 v[140:143], v187 offset:8704
	ds_read_b128 v[144:147], v187 offset:10752
	ds_read_b128 v[148:151], v187 offset:11776
	s_add_i32 s54, s4, 0xfffffe00
	s_addk_i32 s4, 0xfa00
	s_waitcnt lgkmcnt(3)
	v_cndmask_b32_e64 v157, 0, v136, s[8:9]
	s_waitcnt lgkmcnt(2)
	v_cndmask_b32_e64 v161, 0, v140, s[10:11]
	s_waitcnt lgkmcnt(0)
	v_pk_fma_f32 v[130:131], v[126:127], v[146:147], v[150:151]
	v_pk_fma_f32 v[128:129], v[124:125], v[144:145], v[148:149]
	v_cndmask_b32_e64 v159, 0, v137, s[8:9]
	s_nop 1
	v_fmac_f32_dpp v128, v124, v136 row_shr:1 row_mask:0xf bank_mask:0xf bound_ctrl:1
	v_fmac_f32_dpp v129, v125, v137 row_shr:1 row_mask:0xf bank_mask:0xf bound_ctrl:1
	v_fmac_f32_dpp v128, v124, v140 row_shr:2 row_mask:0xf bank_mask:0xf bound_ctrl:1
	v_fmac_f32_dpp v129, v125, v141 row_shr:2 row_mask:0xf bank_mask:0xf bound_ctrl:1
	v_fmac_f32_dpp v130, v126, v138 row_shr:1 row_mask:0xf bank_mask:0xf bound_ctrl:1
	v_fmac_f32_dpp v131, v127, v139 row_shr:1 row_mask:0xf bank_mask:0xf bound_ctrl:1
	v_fmac_f32_dpp v130, v126, v142 row_shr:2 row_mask:0xf bank_mask:0xf bound_ctrl:1
	v_fmac_f32_dpp v131, v127, v143 row_shr:2 row_mask:0xf bank_mask:0xf bound_ctrl:1
	v_cndmask_b32_e64 v163, 0, v141, s[10:11]
	v_cndmask_b32_e64 v158, 0, v138, s[8:9]
	v_cndmask_b32_e64 v162, 0, v142, s[10:11]
	v_cndmask_b32_e64 v156, 0, v139, s[8:9]
	v_cndmask_b32_e64 v160, 0, v143, s[10:11]
	v_add_u32_e32 v154, s54, v189
	v_add_u32_e32 v155, s4, v189
	v_fmac_f32_dpp v128, v112, v157 row_ror:1 row_mask:0xf bank_mask:0xf
	v_fmac_f32_dpp v129, v113, v159 row_ror:1 row_mask:0xf bank_mask:0xf
	v_fmac_f32_dpp v128, v112, v161 row_ror:2 row_mask:0xf bank_mask:0xf
	v_fmac_f32_dpp v129, v113, v163 row_ror:2 row_mask:0xf bank_mask:0xf
	v_fmac_f32_dpp v130, v114, v158 row_ror:1 row_mask:0xf bank_mask:0xf
	v_fmac_f32_dpp v131, v115, v156 row_ror:1 row_mask:0xf bank_mask:0xf
	v_fmac_f32_dpp v130, v114, v162 row_ror:2 row_mask:0xf bank_mask:0xf
	v_fmac_f32_dpp v131, v115, v160 row_ror:2 row_mask:0xf bank_mask:0xf
	s_nop 0
	v_pk_fma_f32 v[126:127], v[114:115], v[146:147], v[150:151]
	v_pk_fma_f32 v[124:125], v[112:113], v[144:145], v[148:149]
	s_nop 0
	s_nop 1
	v_fmac_f32_dpp v124, v112, v136 row_shr:1 row_mask:0xf bank_mask:0xf bound_ctrl:1
	v_fmac_f32_dpp v125, v113, v137 row_shr:1 row_mask:0xf bank_mask:0xf bound_ctrl:1
	v_fmac_f32_dpp v124, v112, v140 row_shr:2 row_mask:0xf bank_mask:0xf bound_ctrl:1
	v_fmac_f32_dpp v125, v113, v141 row_shr:2 row_mask:0xf bank_mask:0xf bound_ctrl:1
	v_mov_b32_e32 v112, v127
	s_nop 1
	v_fmac_f32_dpp v126, v114, v138 row_shr:1 row_mask:0xf bank_mask:0xf bound_ctrl:1
	v_fmac_f32_dpp v112, v115, v139 row_shr:1 row_mask:0xf bank_mask:0xf bound_ctrl:1
	v_fmac_f32_dpp v126, v114, v142 row_shr:2 row_mask:0xf bank_mask:0xf bound_ctrl:1
	v_fmac_f32_dpp v112, v115, v143 row_shr:2 row_mask:0xf bank_mask:0xf bound_ctrl:1
	v_fmac_f32_dpp v124, v100, v157 row_ror:1 row_mask:0xf bank_mask:0xf
	v_fmac_f32_dpp v125, v101, v159 row_ror:1 row_mask:0xf bank_mask:0xf
	v_fmac_f32_dpp v124, v100, v161 row_ror:2 row_mask:0xf bank_mask:0xf
	v_fmac_f32_dpp v125, v101, v163 row_ror:2 row_mask:0xf bank_mask:0xf
	s_nop 0
	v_fmac_f32_dpp v126, v102, v158 row_ror:1 row_mask:0xf bank_mask:0xf
	v_fmac_f32_dpp v112, v103, v156 row_ror:1 row_mask:0xf bank_mask:0xf
	v_fmac_f32_dpp v126, v102, v162 row_ror:2 row_mask:0xf bank_mask:0xf
	v_fmac_f32_dpp v112, v103, v160 row_ror:2 row_mask:0xf bank_mask:0xf
	s_nop 0
	v_mov_b32_e32 v127, v112
	v_pk_fma_f32 v[114:115], v[102:103], v[146:147], v[150:151]
	v_pk_fma_f32 v[112:113], v[100:101], v[144:145], v[148:149]
	s_nop 0
	s_nop 1
	v_fmac_f32_dpp v112, v100, v136 row_shr:1 row_mask:0xf bank_mask:0xf bound_ctrl:1
	v_fmac_f32_dpp v113, v101, v137 row_shr:1 row_mask:0xf bank_mask:0xf bound_ctrl:1
	v_fmac_f32_dpp v112, v100, v140 row_shr:2 row_mask:0xf bank_mask:0xf bound_ctrl:1
	v_fmac_f32_dpp v113, v101, v141 row_shr:2 row_mask:0xf bank_mask:0xf bound_ctrl:1
	v_fmac_f32_dpp v114, v102, v138 row_shr:1 row_mask:0xf bank_mask:0xf bound_ctrl:1
	v_fmac_f32_dpp v115, v103, v139 row_shr:1 row_mask:0xf bank_mask:0xf bound_ctrl:1
	v_fmac_f32_dpp v114, v102, v142 row_shr:2 row_mask:0xf bank_mask:0xf bound_ctrl:1
	v_fmac_f32_dpp v115, v103, v143 row_shr:2 row_mask:0xf bank_mask:0xf bound_ctrl:1
	s_nop 0
	v_fmac_f32_dpp v112, v88, v157 row_ror:1 row_mask:0xf bank_mask:0xf
	v_fmac_f32_dpp v113, v89, v159 row_ror:1 row_mask:0xf bank_mask:0xf
	v_fmac_f32_dpp v112, v88, v161 row_ror:2 row_mask:0xf bank_mask:0xf
	v_fmac_f32_dpp v113, v89, v163 row_ror:2 row_mask:0xf bank_mask:0xf
	v_fmac_f32_dpp v114, v90, v158 row_ror:1 row_mask:0xf bank_mask:0xf
	v_fmac_f32_dpp v115, v91, v156 row_ror:1 row_mask:0xf bank_mask:0xf
	v_fmac_f32_dpp v114, v90, v162 row_ror:2 row_mask:0xf bank_mask:0xf
	v_fmac_f32_dpp v115, v91, v160 row_ror:2 row_mask:0xf bank_mask:0xf
	s_nop 0
	v_pk_fma_f32 v[100:101], v[90:91], v[146:147], v[150:151]
	v_pk_fma_f32 v[102:103], v[88:89], v[144:145], v[148:149]
	v_mov_b32_e32 v134, v100
	v_mov_b32_e32 v132, v102
	s_nop 1
	v_fmac_f32_dpp v132, v88, v136 row_shr:1 row_mask:0xf bank_mask:0xf bound_ctrl:1
	v_fmac_f32_dpp v103, v89, v137 row_shr:1 row_mask:0xf bank_mask:0xf bound_ctrl:1
	v_fmac_f32_dpp v132, v88, v140 row_shr:2 row_mask:0xf bank_mask:0xf bound_ctrl:1
	v_fmac_f32_dpp v103, v89, v141 row_shr:2 row_mask:0xf bank_mask:0xf bound_ctrl:1
	v_fmac_f32_dpp v134, v90, v138 row_shr:1 row_mask:0xf bank_mask:0xf bound_ctrl:1
	v_fmac_f32_dpp v101, v91, v139 row_shr:1 row_mask:0xf bank_mask:0xf bound_ctrl:1
	v_fmac_f32_dpp v134, v90, v142 row_shr:2 row_mask:0xf bank_mask:0xf bound_ctrl:1
	v_fmac_f32_dpp v101, v91, v143 row_shr:2 row_mask:0xf bank_mask:0xf bound_ctrl:1
	s_and_b64 vcc, exec, s[12:13]
	v_mov_b32_e32 v133, v103
	v_mov_b32_e32 v135, v101
	s_cbranch_vccnz .LBB0_400
	ds_read_b128 v[88:91], v154
	ds_read_b128 v[164:167], v155
	s_waitcnt lgkmcnt(0)
	v_cndmask_b32_e64 v100, v88, v164, s[8:9]
	v_mul_f32_e32 v100, v161, v100
	v_fmac_f32_e32 v100, v157, v88
	v_cndmask_b32_e64 v88, v90, v166, s[8:9]
	v_mul_f32_e32 v88, v162, v88
	v_fmac_f32_e32 v88, v158, v90
	v_cndmask_b32_e64 v102, v89, v165, s[8:9]
	v_add_f32_e32 v134, v134, v88
	v_cndmask_b32_e64 v88, v91, v167, s[8:9]
	v_mul_f32_e32 v102, v163, v102
	v_mul_f32_e32 v88, v160, v88
	v_fmac_f32_e32 v102, v159, v89
	v_fmac_f32_e32 v88, v156, v91
	v_add_f32_e32 v132, v132, v100
	v_add_f32_e32 v133, v103, v102
	v_add_f32_e32 v135, v101, v88
.LBB0_400:
	v_pk_fma_f32 v[90:91], v[118:119], v[146:147], v[150:151]
	v_pk_fma_f32 v[88:89], v[116:117], v[144:145], v[148:149]
	s_add_i32 s4, s5, 0xfffffe00
	s_addk_i32 s5, 0xfa00
	v_fmac_f32_dpp v88, v116, v136 row_shr:1 row_mask:0xf bank_mask:0xf bound_ctrl:1
	v_fmac_f32_dpp v89, v117, v137 row_shr:1 row_mask:0xf bank_mask:0xf bound_ctrl:1
	v_fmac_f32_dpp v88, v116, v140 row_shr:2 row_mask:0xf bank_mask:0xf bound_ctrl:1
	v_fmac_f32_dpp v89, v117, v141 row_shr:2 row_mask:0xf bank_mask:0xf bound_ctrl:1
	v_fmac_f32_dpp v90, v118, v138 row_shr:1 row_mask:0xf bank_mask:0xf bound_ctrl:1
	v_fmac_f32_dpp v91, v119, v139 row_shr:1 row_mask:0xf bank_mask:0xf bound_ctrl:1
	v_fmac_f32_dpp v90, v118, v142 row_shr:2 row_mask:0xf bank_mask:0xf bound_ctrl:1
	v_fmac_f32_dpp v91, v119, v143 row_shr:2 row_mask:0xf bank_mask:0xf bound_ctrl:1
	v_add_u32_e32 v152, s4, v189
	v_add_u32_e32 v153, s5, v189
	v_fmac_f32_dpp v88, v104, v157 row_ror:1 row_mask:0xf bank_mask:0xf
	v_fmac_f32_dpp v89, v105, v159 row_ror:1 row_mask:0xf bank_mask:0xf
	v_fmac_f32_dpp v88, v104, v161 row_ror:2 row_mask:0xf bank_mask:0xf
	v_fmac_f32_dpp v89, v105, v163 row_ror:2 row_mask:0xf bank_mask:0xf
	v_fmac_f32_dpp v90, v106, v158 row_ror:1 row_mask:0xf bank_mask:0xf
	v_fmac_f32_dpp v91, v107, v156 row_ror:1 row_mask:0xf bank_mask:0xf
	v_fmac_f32_dpp v90, v106, v162 row_ror:2 row_mask:0xf bank_mask:0xf
	v_fmac_f32_dpp v91, v107, v160 row_ror:2 row_mask:0xf bank_mask:0xf
	s_nop 0
	v_pk_fma_f32 v[102:103], v[106:107], v[146:147], v[150:151]
	v_pk_fma_f32 v[100:101], v[104:105], v[144:145], v[148:149]
	s_nop 0
	s_nop 1
	v_fmac_f32_dpp v100, v104, v136 row_shr:1 row_mask:0xf bank_mask:0xf bound_ctrl:1
	v_fmac_f32_dpp v101, v105, v137 row_shr:1 row_mask:0xf bank_mask:0xf bound_ctrl:1
	v_fmac_f32_dpp v100, v104, v140 row_shr:2 row_mask:0xf bank_mask:0xf bound_ctrl:1
	v_fmac_f32_dpp v101, v105, v141 row_shr:2 row_mask:0xf bank_mask:0xf bound_ctrl:1
	v_fmac_f32_dpp v102, v106, v138 row_shr:1 row_mask:0xf bank_mask:0xf bound_ctrl:1
	v_fmac_f32_dpp v103, v107, v139 row_shr:1 row_mask:0xf bank_mask:0xf bound_ctrl:1
	v_fmac_f32_dpp v102, v106, v142 row_shr:2 row_mask:0xf bank_mask:0xf bound_ctrl:1
	v_fmac_f32_dpp v103, v107, v143 row_shr:2 row_mask:0xf bank_mask:0xf bound_ctrl:1
	s_nop 0
	v_fmac_f32_dpp v100, v92, v157 row_ror:1 row_mask:0xf bank_mask:0xf
	v_fmac_f32_dpp v101, v93, v159 row_ror:1 row_mask:0xf bank_mask:0xf
	v_fmac_f32_dpp v100, v92, v161 row_ror:2 row_mask:0xf bank_mask:0xf
	v_fmac_f32_dpp v101, v93, v163 row_ror:2 row_mask:0xf bank_mask:0xf
	v_fmac_f32_dpp v102, v94, v158 row_ror:1 row_mask:0xf bank_mask:0xf
	v_fmac_f32_dpp v103, v95, v156 row_ror:1 row_mask:0xf bank_mask:0xf
	v_fmac_f32_dpp v102, v94, v162 row_ror:2 row_mask:0xf bank_mask:0xf
	v_fmac_f32_dpp v103, v95, v160 row_ror:2 row_mask:0xf bank_mask:0xf
	s_nop 0
	v_pk_fma_f32 v[106:107], v[94:95], v[146:147], v[150:151]
	v_pk_fma_f32 v[104:105], v[92:93], v[144:145], v[148:149]
	s_nop 0
	s_nop 1
	v_fmac_f32_dpp v104, v92, v136 row_shr:1 row_mask:0xf bank_mask:0xf bound_ctrl:1
	v_fmac_f32_dpp v105, v93, v137 row_shr:1 row_mask:0xf bank_mask:0xf bound_ctrl:1
	v_fmac_f32_dpp v104, v92, v140 row_shr:2 row_mask:0xf bank_mask:0xf bound_ctrl:1
	v_fmac_f32_dpp v105, v93, v141 row_shr:2 row_mask:0xf bank_mask:0xf bound_ctrl:1
	v_fmac_f32_dpp v106, v94, v138 row_shr:1 row_mask:0xf bank_mask:0xf bound_ctrl:1
	v_fmac_f32_dpp v107, v95, v139 row_shr:1 row_mask:0xf bank_mask:0xf bound_ctrl:1
	v_fmac_f32_dpp v106, v94, v142 row_shr:2 row_mask:0xf bank_mask:0xf bound_ctrl:1
	v_fmac_f32_dpp v107, v95, v143 row_shr:2 row_mask:0xf bank_mask:0xf bound_ctrl:1
	s_nop 0
	v_fmac_f32_dpp v104, v76, v157 row_ror:1 row_mask:0xf bank_mask:0xf
	v_fmac_f32_dpp v105, v77, v159 row_ror:1 row_mask:0xf bank_mask:0xf
	v_fmac_f32_dpp v104, v76, v161 row_ror:2 row_mask:0xf bank_mask:0xf
	v_fmac_f32_dpp v105, v77, v163 row_ror:2 row_mask:0xf bank_mask:0xf
	v_fmac_f32_dpp v106, v78, v158 row_ror:1 row_mask:0xf bank_mask:0xf
	v_fmac_f32_dpp v107, v79, v156 row_ror:1 row_mask:0xf bank_mask:0xf
	v_fmac_f32_dpp v106, v78, v162 row_ror:2 row_mask:0xf bank_mask:0xf
	v_fmac_f32_dpp v107, v79, v160 row_ror:2 row_mask:0xf bank_mask:0xf
	s_nop 0
	v_pk_fma_f32 v[94:95], v[78:79], v[146:147], v[150:151]
	v_pk_fma_f32 v[92:93], v[76:77], v[144:145], v[148:149]
	s_and_b64 vcc, exec, s[14:15]
	s_nop 1
	v_fmac_f32_dpp v92, v76, v136 row_shr:1 row_mask:0xf bank_mask:0xf bound_ctrl:1
	v_fmac_f32_dpp v93, v77, v137 row_shr:1 row_mask:0xf bank_mask:0xf bound_ctrl:1
	v_fmac_f32_dpp v92, v76, v140 row_shr:2 row_mask:0xf bank_mask:0xf bound_ctrl:1
	v_fmac_f32_dpp v93, v77, v141 row_shr:2 row_mask:0xf bank_mask:0xf bound_ctrl:1
	v_mov_b32_e32 v76, v95
	s_nop 1
	v_fmac_f32_dpp v94, v78, v138 row_shr:1 row_mask:0xf bank_mask:0xf bound_ctrl:1
	v_fmac_f32_dpp v76, v79, v139 row_shr:1 row_mask:0xf bank_mask:0xf bound_ctrl:1
	v_fmac_f32_dpp v94, v78, v142 row_shr:2 row_mask:0xf bank_mask:0xf bound_ctrl:1
	v_fmac_f32_dpp v76, v79, v143 row_shr:2 row_mask:0xf bank_mask:0xf bound_ctrl:1
	s_cbranch_vccnz .LBB0_402
	ds_read_b128 v[116:119], v152
	ds_read_b128 v[136:139], v153
	s_waitcnt lgkmcnt(0)
	v_cndmask_b32_e64 v77, v116, v136, s[8:9]
	v_mul_f32_e32 v77, v161, v77
	v_fmac_f32_e32 v77, v157, v116
	v_add_f32_e32 v92, v92, v77
	v_cndmask_b32_e64 v77, v118, v138, s[8:9]
	v_mul_f32_e32 v77, v162, v77
	v_fmac_f32_e32 v77, v158, v118
	v_cndmask_b32_e64 v78, v117, v137, s[8:9]
	v_add_f32_e32 v94, v94, v77
	v_cndmask_b32_e64 v77, v119, v139, s[8:9]
	v_mul_f32_e32 v78, v163, v78
	v_mul_f32_e32 v77, v160, v77
	v_fmac_f32_e32 v78, v159, v117
	v_fmac_f32_e32 v77, v156, v119
	v_add_f32_e32 v93, v93, v78
	v_add_f32_e32 v95, v76, v77
	s_branch .LBB0_403

.LBB0_403:
	ds_read_b128 v[116:119], v187 offset:9744
	ds_read_b128 v[136:139], v187 offset:8720
	ds_read_b128 v[140:143], v187 offset:10768
	ds_read_b128 v[144:147], v187 offset:11792
	s_waitcnt lgkmcnt(3)
	v_cndmask_b32_e64 v157, 0, v116, s[8:9]
	s_waitcnt lgkmcnt(2)
	v_cndmask_b32_e64 v161, 0, v136, s[10:11]
	v_cndmask_b32_e64 v159, 0, v117, s[8:9]
	s_waitcnt lgkmcnt(0)
	v_pk_fma_f32 v[78:79], v[66:67], v[142:143], v[146:147]
	v_pk_fma_f32 v[76:77], v[64:65], v[140:141], v[144:145]
	v_cndmask_b32_e64 v163, 0, v137, s[10:11]
	s_nop 1
	v_fmac_f32_dpp v76, v64, v116 row_shr:1 row_mask:0xf bank_mask:0xf bound_ctrl:1
	v_fmac_f32_dpp v77, v65, v117 row_shr:1 row_mask:0xf bank_mask:0xf bound_ctrl:1
	v_fmac_f32_dpp v76, v64, v136 row_shr:2 row_mask:0xf bank_mask:0xf bound_ctrl:1
	v_fmac_f32_dpp v77, v65, v137 row_shr:2 row_mask:0xf bank_mask:0xf bound_ctrl:1
	v_fmac_f32_dpp v78, v66, v118 row_shr:1 row_mask:0xf bank_mask:0xf bound_ctrl:1
	v_fmac_f32_dpp v79, v67, v119 row_shr:1 row_mask:0xf bank_mask:0xf bound_ctrl:1
	v_fmac_f32_dpp v78, v66, v138 row_shr:2 row_mask:0xf bank_mask:0xf bound_ctrl:1
	v_fmac_f32_dpp v79, v67, v139 row_shr:2 row_mask:0xf bank_mask:0xf bound_ctrl:1
	v_cndmask_b32_e64 v158, 0, v118, s[8:9]
	v_cndmask_b32_e64 v162, 0, v138, s[10:11]
	v_cndmask_b32_e64 v156, 0, v119, s[8:9]
	v_cndmask_b32_e64 v160, 0, v139, s[10:11]
	v_fmac_f32_dpp v76, v52, v157 row_ror:1 row_mask:0xf bank_mask:0xf
	v_fmac_f32_dpp v77, v53, v159 row_ror:1 row_mask:0xf bank_mask:0xf
	v_fmac_f32_dpp v76, v52, v161 row_ror:2 row_mask:0xf bank_mask:0xf
	v_fmac_f32_dpp v77, v53, v163 row_ror:2 row_mask:0xf bank_mask:0xf
	v_fmac_f32_dpp v78, v54, v158 row_ror:1 row_mask:0xf bank_mask:0xf
	v_fmac_f32_dpp v79, v55, v156 row_ror:1 row_mask:0xf bank_mask:0xf
	v_fmac_f32_dpp v78, v54, v162 row_ror:2 row_mask:0xf bank_mask:0xf
	v_fmac_f32_dpp v79, v55, v160 row_ror:2 row_mask:0xf bank_mask:0xf
	s_nop 0
	v_pk_fma_f32 v[66:67], v[54:55], v[142:143], v[146:147]
	v_pk_fma_f32 v[64:65], v[52:53], v[140:141], v[144:145]
	s_nop 0
	s_nop 1
	v_fmac_f32_dpp v64, v52, v116 row_shr:1 row_mask:0xf bank_mask:0xf bound_ctrl:1
	v_fmac_f32_dpp v65, v53, v117 row_shr:1 row_mask:0xf bank_mask:0xf bound_ctrl:1
	v_fmac_f32_dpp v64, v52, v136 row_shr:2 row_mask:0xf bank_mask:0xf bound_ctrl:1
	v_fmac_f32_dpp v65, v53, v137 row_shr:2 row_mask:0xf bank_mask:0xf bound_ctrl:1
	v_mov_b32_e32 v52, v67
	s_nop 1
	v_fmac_f32_dpp v66, v54, v118 row_shr:1 row_mask:0xf bank_mask:0xf bound_ctrl:1
	v_fmac_f32_dpp v52, v55, v119 row_shr:1 row_mask:0xf bank_mask:0xf bound_ctrl:1
	v_fmac_f32_dpp v66, v54, v138 row_shr:2 row_mask:0xf bank_mask:0xf bound_ctrl:1
	v_fmac_f32_dpp v52, v55, v139 row_shr:2 row_mask:0xf bank_mask:0xf bound_ctrl:1
	v_fmac_f32_dpp v64, v36, v157 row_ror:1 row_mask:0xf bank_mask:0xf
	v_fmac_f32_dpp v65, v37, v159 row_ror:1 row_mask:0xf bank_mask:0xf
	v_fmac_f32_dpp v64, v36, v161 row_ror:2 row_mask:0xf bank_mask:0xf
	v_fmac_f32_dpp v65, v37, v163 row_ror:2 row_mask:0xf bank_mask:0xf
	s_nop 0
	v_fmac_f32_dpp v66, v38, v158 row_ror:1 row_mask:0xf bank_mask:0xf
	v_fmac_f32_dpp v52, v39, v156 row_ror:1 row_mask:0xf bank_mask:0xf
	v_fmac_f32_dpp v66, v38, v162 row_ror:2 row_mask:0xf bank_mask:0xf
	v_fmac_f32_dpp v52, v39, v160 row_ror:2 row_mask:0xf bank_mask:0xf
	s_nop 0
	v_mov_b32_e32 v67, v52
	v_pk_fma_f32 v[54:55], v[38:39], v[142:143], v[146:147]
	v_pk_fma_f32 v[52:53], v[36:37], v[140:141], v[144:145]
	s_nop 0
	s_nop 1
	v_fmac_f32_dpp v52, v36, v116 row_shr:1 row_mask:0xf bank_mask:0xf bound_ctrl:1
	v_fmac_f32_dpp v53, v37, v117 row_shr:1 row_mask:0xf bank_mask:0xf bound_ctrl:1
	v_fmac_f32_dpp v52, v36, v136 row_shr:2 row_mask:0xf bank_mask:0xf bound_ctrl:1
	v_fmac_f32_dpp v53, v37, v137 row_shr:2 row_mask:0xf bank_mask:0xf bound_ctrl:1
	v_mov_b32_e32 v36, v55
	s_nop 1
	v_fmac_f32_dpp v54, v38, v118 row_shr:1 row_mask:0xf bank_mask:0xf bound_ctrl:1
	v_fmac_f32_dpp v36, v39, v119 row_shr:1 row_mask:0xf bank_mask:0xf bound_ctrl:1
	v_fmac_f32_dpp v54, v38, v138 row_shr:2 row_mask:0xf bank_mask:0xf bound_ctrl:1
	v_fmac_f32_dpp v36, v39, v139 row_shr:2 row_mask:0xf bank_mask:0xf bound_ctrl:1
	v_fmac_f32_dpp v52, v24, v157 row_ror:1 row_mask:0xf bank_mask:0xf
	v_fmac_f32_dpp v53, v25, v159 row_ror:1 row_mask:0xf bank_mask:0xf
	v_fmac_f32_dpp v52, v24, v161 row_ror:2 row_mask:0xf bank_mask:0xf
	v_fmac_f32_dpp v53, v25, v163 row_ror:2 row_mask:0xf bank_mask:0xf
	s_nop 0
	v_fmac_f32_dpp v54, v26, v158 row_ror:1 row_mask:0xf bank_mask:0xf
	v_fmac_f32_dpp v36, v27, v156 row_ror:1 row_mask:0xf bank_mask:0xf
	v_fmac_f32_dpp v54, v26, v162 row_ror:2 row_mask:0xf bank_mask:0xf
	v_fmac_f32_dpp v36, v27, v160 row_ror:2 row_mask:0xf bank_mask:0xf
	s_nop 0
	v_mov_b32_e32 v55, v36
	v_pk_fma_f32 v[36:37], v[26:27], v[142:143], v[146:147]
	v_pk_fma_f32 v[38:39], v[24:25], v[140:141], v[144:145]
	v_mov_b32_e32 v150, v36
	v_mov_b32_e32 v148, v38
	s_nop 1
	v_fmac_f32_dpp v148, v24, v116 row_shr:1 row_mask:0xf bank_mask:0xf bound_ctrl:1
	v_fmac_f32_dpp v39, v25, v117 row_shr:1 row_mask:0xf bank_mask:0xf bound_ctrl:1
	v_fmac_f32_dpp v148, v24, v136 row_shr:2 row_mask:0xf bank_mask:0xf bound_ctrl:1
	v_fmac_f32_dpp v39, v25, v137 row_shr:2 row_mask:0xf bank_mask:0xf bound_ctrl:1
	v_fmac_f32_dpp v150, v26, v118 row_shr:1 row_mask:0xf bank_mask:0xf bound_ctrl:1
	v_fmac_f32_dpp v37, v27, v119 row_shr:1 row_mask:0xf bank_mask:0xf bound_ctrl:1
	v_fmac_f32_dpp v150, v26, v138 row_shr:2 row_mask:0xf bank_mask:0xf bound_ctrl:1
	v_fmac_f32_dpp v37, v27, v139 row_shr:2 row_mask:0xf bank_mask:0xf bound_ctrl:1
	s_and_b64 vcc, exec, s[12:13]
	v_mov_b32_e32 v149, v39
	v_mov_b32_e32 v151, v37
	s_cbranch_vccnz .LBB0_405
	ds_read_b128 v[24:27], v154 offset:16
	ds_read_b128 v[164:167], v155 offset:16
	s_waitcnt lgkmcnt(0)
	v_cndmask_b32_e64 v36, v24, v164, s[8:9]
	v_mul_f32_e32 v36, v161, v36
	v_fmac_f32_e32 v36, v157, v24
	v_cndmask_b32_e64 v24, v26, v166, s[8:9]
	v_mul_f32_e32 v24, v162, v24
	v_fmac_f32_e32 v24, v158, v26
	v_cndmask_b32_e64 v38, v25, v165, s[8:9]
	v_add_f32_e32 v150, v150, v24
	v_cndmask_b32_e64 v24, v27, v167, s[8:9]
	v_mul_f32_e32 v38, v163, v38
	v_mul_f32_e32 v24, v160, v24
	v_fmac_f32_e32 v38, v159, v25
	v_fmac_f32_e32 v24, v156, v27
	v_add_f32_e32 v148, v148, v36
	v_add_f32_e32 v149, v39, v38
	v_add_f32_e32 v151, v37, v24
.LBB0_405:
	v_pk_fma_f32 v[26:27], v[58:59], v[142:143], v[146:147]
	v_pk_fma_f32 v[24:25], v[56:57], v[140:141], v[144:145]
	s_nop 0
	s_nop 1
	v_fmac_f32_dpp v24, v56, v116 row_shr:1 row_mask:0xf bank_mask:0xf bound_ctrl:1
	v_fmac_f32_dpp v25, v57, v117 row_shr:1 row_mask:0xf bank_mask:0xf bound_ctrl:1
	v_fmac_f32_dpp v24, v56, v136 row_shr:2 row_mask:0xf bank_mask:0xf bound_ctrl:1
	v_fmac_f32_dpp v25, v57, v137 row_shr:2 row_mask:0xf bank_mask:0xf bound_ctrl:1
	v_fmac_f32_dpp v26, v58, v118 row_shr:1 row_mask:0xf bank_mask:0xf bound_ctrl:1
	v_fmac_f32_dpp v27, v59, v119 row_shr:1 row_mask:0xf bank_mask:0xf bound_ctrl:1
	v_fmac_f32_dpp v26, v58, v138 row_shr:2 row_mask:0xf bank_mask:0xf bound_ctrl:1
	v_fmac_f32_dpp v27, v59, v139 row_shr:2 row_mask:0xf bank_mask:0xf bound_ctrl:1
	s_nop 0
	v_fmac_f32_dpp v24, v44, v157 row_ror:1 row_mask:0xf bank_mask:0xf
	v_fmac_f32_dpp v25, v45, v159 row_ror:1 row_mask:0xf bank_mask:0xf
	v_fmac_f32_dpp v24, v44, v161 row_ror:2 row_mask:0xf bank_mask:0xf
	v_fmac_f32_dpp v25, v45, v163 row_ror:2 row_mask:0xf bank_mask:0xf
	v_fmac_f32_dpp v26, v46, v158 row_ror:1 row_mask:0xf bank_mask:0xf
	v_fmac_f32_dpp v27, v47, v156 row_ror:1 row_mask:0xf bank_mask:0xf
	v_fmac_f32_dpp v26, v46, v162 row_ror:2 row_mask:0xf bank_mask:0xf
	v_fmac_f32_dpp v27, v47, v160 row_ror:2 row_mask:0xf bank_mask:0xf
	s_nop 0
	v_pk_fma_f32 v[38:39], v[46:47], v[142:143], v[146:147]
	v_pk_fma_f32 v[36:37], v[44:45], v[140:141], v[144:145]
	s_nop 0
	s_nop 1
	v_fmac_f32_dpp v36, v44, v116 row_shr:1 row_mask:0xf bank_mask:0xf bound_ctrl:1
	v_fmac_f32_dpp v37, v45, v117 row_shr:1 row_mask:0xf bank_mask:0xf bound_ctrl:1
	v_fmac_f32_dpp v36, v44, v136 row_shr:2 row_mask:0xf bank_mask:0xf bound_ctrl:1
	v_fmac_f32_dpp v37, v45, v137 row_shr:2 row_mask:0xf bank_mask:0xf bound_ctrl:1
	v_fmac_f32_dpp v38, v46, v118 row_shr:1 row_mask:0xf bank_mask:0xf bound_ctrl:1
	v_fmac_f32_dpp v39, v47, v119 row_shr:1 row_mask:0xf bank_mask:0xf bound_ctrl:1
	v_fmac_f32_dpp v38, v46, v138 row_shr:2 row_mask:0xf bank_mask:0xf bound_ctrl:1
	v_fmac_f32_dpp v39, v47, v139 row_shr:2 row_mask:0xf bank_mask:0xf bound_ctrl:1
	s_nop 0
	v_fmac_f32_dpp v36, v28, v157 row_ror:1 row_mask:0xf bank_mask:0xf
	v_fmac_f32_dpp v37, v29, v159 row_ror:1 row_mask:0xf bank_mask:0xf
	v_fmac_f32_dpp v36, v28, v161 row_ror:2 row_mask:0xf bank_mask:0xf
	v_fmac_f32_dpp v37, v29, v163 row_ror:2 row_mask:0xf bank_mask:0xf
	v_fmac_f32_dpp v38, v30, v158 row_ror:1 row_mask:0xf bank_mask:0xf
	v_fmac_f32_dpp v39, v31, v156 row_ror:1 row_mask:0xf bank_mask:0xf
	v_fmac_f32_dpp v38, v30, v162 row_ror:2 row_mask:0xf bank_mask:0xf
	v_fmac_f32_dpp v39, v31, v160 row_ror:2 row_mask:0xf bank_mask:0xf
	s_nop 0
	v_pk_fma_f32 v[46:47], v[30:31], v[142:143], v[146:147]
	v_pk_fma_f32 v[44:45], v[28:29], v[140:141], v[144:145]
	s_nop 0
	s_nop 1
	v_fmac_f32_dpp v44, v28, v116 row_shr:1 row_mask:0xf bank_mask:0xf bound_ctrl:1
	v_fmac_f32_dpp v45, v29, v117 row_shr:1 row_mask:0xf bank_mask:0xf bound_ctrl:1
	v_fmac_f32_dpp v44, v28, v136 row_shr:2 row_mask:0xf bank_mask:0xf bound_ctrl:1
	v_fmac_f32_dpp v45, v29, v137 row_shr:2 row_mask:0xf bank_mask:0xf bound_ctrl:1
	v_fmac_f32_dpp v46, v30, v118 row_shr:1 row_mask:0xf bank_mask:0xf bound_ctrl:1
	v_fmac_f32_dpp v47, v31, v119 row_shr:1 row_mask:0xf bank_mask:0xf bound_ctrl:1
	v_fmac_f32_dpp v46, v30, v138 row_shr:2 row_mask:0xf bank_mask:0xf bound_ctrl:1
	v_fmac_f32_dpp v47, v31, v139 row_shr:2 row_mask:0xf bank_mask:0xf bound_ctrl:1
	s_nop 0
	v_fmac_f32_dpp v44, v12, v157 row_ror:1 row_mask:0xf bank_mask:0xf
	v_fmac_f32_dpp v45, v13, v159 row_ror:1 row_mask:0xf bank_mask:0xf
	v_fmac_f32_dpp v44, v12, v161 row_ror:2 row_mask:0xf bank_mask:0xf
	v_fmac_f32_dpp v45, v13, v163 row_ror:2 row_mask:0xf bank_mask:0xf
	v_fmac_f32_dpp v46, v14, v158 row_ror:1 row_mask:0xf bank_mask:0xf
	v_fmac_f32_dpp v47, v15, v156 row_ror:1 row_mask:0xf bank_mask:0xf
	v_fmac_f32_dpp v46, v14, v162 row_ror:2 row_mask:0xf bank_mask:0xf
	v_fmac_f32_dpp v47, v15, v160 row_ror:2 row_mask:0xf bank_mask:0xf
	s_nop 0
	v_pk_fma_f32 v[30:31], v[14:15], v[142:143], v[146:147]
	v_pk_fma_f32 v[28:29], v[12:13], v[140:141], v[144:145]
	s_and_b64 vcc, exec, s[14:15]
	s_nop 1
	v_fmac_f32_dpp v28, v12, v116 row_shr:1 row_mask:0xf bank_mask:0xf bound_ctrl:1
	v_fmac_f32_dpp v29, v13, v117 row_shr:1 row_mask:0xf bank_mask:0xf bound_ctrl:1
	v_fmac_f32_dpp v28, v12, v136 row_shr:2 row_mask:0xf bank_mask:0xf bound_ctrl:1
	v_fmac_f32_dpp v29, v13, v137 row_shr:2 row_mask:0xf bank_mask:0xf bound_ctrl:1
	v_fmac_f32_dpp v30, v14, v118 row_shr:1 row_mask:0xf bank_mask:0xf bound_ctrl:1
	v_fmac_f32_dpp v31, v15, v119 row_shr:1 row_mask:0xf bank_mask:0xf bound_ctrl:1
	v_fmac_f32_dpp v30, v14, v138 row_shr:2 row_mask:0xf bank_mask:0xf bound_ctrl:1
	v_fmac_f32_dpp v31, v15, v139 row_shr:2 row_mask:0xf bank_mask:0xf bound_ctrl:1
	s_cbranch_vccnz .LBB0_407
	ds_read_b128 v[12:15], v152 offset:16
	ds_read_b128 v[56:59], v153 offset:16
	s_waitcnt lgkmcnt(0)
	v_cndmask_b32_e64 v56, v12, v56, s[8:9]
	v_mul_f32_e32 v56, v161, v56
	v_fmac_f32_e32 v56, v157, v12
	v_cndmask_b32_e64 v12, v14, v58, s[8:9]
	v_mul_f32_e32 v12, v162, v12
	v_fmac_f32_e32 v12, v158, v14
	v_cndmask_b32_e64 v57, v13, v57, s[8:9]
	v_add_f32_e32 v30, v30, v12
	v_cndmask_b32_e64 v12, v15, v59, s[8:9]
	v_mul_f32_e32 v57, v163, v57
	v_mul_f32_e32 v12, v160, v12
	v_fmac_f32_e32 v57, v159, v13
	v_fmac_f32_e32 v12, v156, v15
	v_add_f32_e32 v28, v28, v56
	v_add_f32_e32 v29, v29, v57
	v_add_f32_e32 v31, v31, v12

.LBB0_1000:
	s_or_b64 exec, exec, s[8:9]
	s_waitcnt lgkmcnt(0)
	s_barrier
	v_add_u32_e32 v187, s5, v189
	ds_read_b128 v[148:151], v187 offset:9216
	ds_read_b128 v[152:155], v187 offset:8192
	ds_read_b128 v[40:43], v187 offset:10240
	ds_read_b128 v[160:163], v187 offset:11264
	s_add_i32 s4, s5, s79
	s_add_i32 s12, s4, 0xfffffc00
	v_cmp_eq_u32_e64 s[8:9], 0, v210
	v_cmp_gt_u32_e64 s[10:11], 2, v210
	s_waitcnt lgkmcnt(0)
	v_pk_fma_f32 v[6:7], v[166:167], v[42:43], v[162:163]
	v_pk_fma_f32 v[4:5], v[164:165], v[40:41], v[160:161]
	v_add_u32_e32 v191, s12, v189
	s_add_i32 s12, s4, 0xfffff800
	v_fmac_f32_dpp v4, v164, v148 row_shr:1 row_mask:0xf bank_mask:0xf bound_ctrl:1
	v_fmac_f32_dpp v5, v165, v149 row_shr:1 row_mask:0xf bank_mask:0xf bound_ctrl:1
	v_fmac_f32_dpp v4, v164, v152 row_shr:2 row_mask:0xf bank_mask:0xf bound_ctrl:1
	v_fmac_f32_dpp v5, v165, v153 row_shr:2 row_mask:0xf bank_mask:0xf bound_ctrl:1
	v_fmac_f32_dpp v6, v166, v150 row_shr:1 row_mask:0xf bank_mask:0xf bound_ctrl:1
	v_fmac_f32_dpp v7, v167, v151 row_shr:1 row_mask:0xf bank_mask:0xf bound_ctrl:1
	v_fmac_f32_dpp v6, v166, v154 row_shr:2 row_mask:0xf bank_mask:0xf bound_ctrl:1
	v_fmac_f32_dpp v7, v167, v155 row_shr:2 row_mask:0xf bank_mask:0xf bound_ctrl:1
	v_cndmask_b32_e64 v195, 0, v148, s[8:9]
	v_cndmask_b32_e64 v211, 0, v152, s[10:11]
	v_cndmask_b32_e64 v201, 0, v149, s[8:9]
	v_cndmask_b32_e64 v213, 0, v153, s[10:11]
	v_cndmask_b32_e64 v199, 0, v150, s[8:9]
	v_cndmask_b32_e64 v212, 0, v154, s[10:11]
	v_cndmask_b32_e64 v197, 0, v151, s[8:9]
	v_cndmask_b32_e64 v210, 0, v155, s[10:11]
	v_add_u32_e32 v193, s12, v189
	v_fmac_f32_dpp v4, v156, v195 row_ror:1 row_mask:0xf bank_mask:0xf
	v_fmac_f32_dpp v5, v157, v201 row_ror:1 row_mask:0xf bank_mask:0xf
	v_fmac_f32_dpp v4, v156, v211 row_ror:2 row_mask:0xf bank_mask:0xf
	v_fmac_f32_dpp v5, v157, v213 row_ror:2 row_mask:0xf bank_mask:0xf
	v_fmac_f32_dpp v6, v158, v199 row_ror:1 row_mask:0xf bank_mask:0xf
	v_fmac_f32_dpp v7, v159, v197 row_ror:1 row_mask:0xf bank_mask:0xf
	v_fmac_f32_dpp v6, v158, v212 row_ror:2 row_mask:0xf bank_mask:0xf
	v_fmac_f32_dpp v7, v159, v210 row_ror:2 row_mask:0xf bank_mask:0xf
	s_nop 0
	v_pk_fma_f32 v[16:17], v[156:157], v[40:41], v[160:161]
	v_pk_fma_f32 v[18:19], v[158:159], v[42:43], v[162:163]
	v_mov_b32_e32 v0, v17
	s_nop 1
	v_fmac_f32_dpp v16, v156, v148 row_shr:1 row_mask:0xf bank_mask:0xf bound_ctrl:1
	v_fmac_f32_dpp v0, v157, v149 row_shr:1 row_mask:0xf bank_mask:0xf bound_ctrl:1
	v_fmac_f32_dpp v16, v156, v152 row_shr:2 row_mask:0xf bank_mask:0xf bound_ctrl:1
	v_fmac_f32_dpp v0, v157, v153 row_shr:2 row_mask:0xf bank_mask:0xf bound_ctrl:1
	v_fmac_f32_dpp v18, v158, v150 row_shr:1 row_mask:0xf bank_mask:0xf bound_ctrl:1
	v_fmac_f32_dpp v19, v159, v151 row_shr:1 row_mask:0xf bank_mask:0xf bound_ctrl:1
	v_fmac_f32_dpp v18, v158, v154 row_shr:2 row_mask:0xf bank_mask:0xf bound_ctrl:1
	v_fmac_f32_dpp v19, v159, v155 row_shr:2 row_mask:0xf bank_mask:0xf bound_ctrl:1
	s_nop 0
	v_fmac_f32_dpp v16, v144, v195 row_ror:1 row_mask:0xf bank_mask:0xf
	v_fmac_f32_dpp v0, v145, v201 row_ror:1 row_mask:0xf bank_mask:0xf
	v_fmac_f32_dpp v16, v144, v211 row_ror:2 row_mask:0xf bank_mask:0xf
	v_fmac_f32_dpp v0, v145, v213 row_ror:2 row_mask:0xf bank_mask:0xf
	v_fmac_f32_dpp v18, v146, v199 row_ror:1 row_mask:0xf bank_mask:0xf
	v_fmac_f32_dpp v19, v147, v197 row_ror:1 row_mask:0xf bank_mask:0xf
	v_fmac_f32_dpp v18, v146, v212 row_ror:2 row_mask:0xf bank_mask:0xf
	v_fmac_f32_dpp v19, v147, v210 row_ror:2 row_mask:0xf bank_mask:0xf
	s_nop 0
	v_mov_b32_e32 v17, v0
	v_pk_fma_f32 v[34:35], v[146:147], v[42:43], v[162:163]
	v_pk_fma_f32 v[32:33], v[144:145], v[40:41], v[160:161]
	v_mov_b32_e32 v0, v35
	s_nop 1
	v_fmac_f32_dpp v32, v144, v148 row_shr:1 row_mask:0xf bank_mask:0xf bound_ctrl:1
	v_fmac_f32_dpp v33, v145, v149 row_shr:1 row_mask:0xf bank_mask:0xf bound_ctrl:1
	v_fmac_f32_dpp v32, v144, v152 row_shr:2 row_mask:0xf bank_mask:0xf bound_ctrl:1
	v_fmac_f32_dpp v33, v145, v153 row_shr:2 row_mask:0xf bank_mask:0xf bound_ctrl:1
	v_fmac_f32_dpp v34, v146, v150 row_shr:1 row_mask:0xf bank_mask:0xf bound_ctrl:1
	v_fmac_f32_dpp v0, v147, v151 row_shr:1 row_mask:0xf bank_mask:0xf bound_ctrl:1
	v_fmac_f32_dpp v34, v146, v154 row_shr:2 row_mask:0xf bank_mask:0xf bound_ctrl:1
	v_fmac_f32_dpp v0, v147, v155 row_shr:2 row_mask:0xf bank_mask:0xf bound_ctrl:1
	s_nop 0
	v_fmac_f32_dpp v32, v140, v195 row_ror:1 row_mask:0xf bank_mask:0xf
	v_fmac_f32_dpp v33, v141, v201 row_ror:1 row_mask:0xf bank_mask:0xf
	v_fmac_f32_dpp v32, v140, v211 row_ror:2 row_mask:0xf bank_mask:0xf
	v_fmac_f32_dpp v33, v141, v213 row_ror:2 row_mask:0xf bank_mask:0xf
	v_fmac_f32_dpp v34, v142, v199 row_ror:1 row_mask:0xf bank_mask:0xf
	v_fmac_f32_dpp v0, v143, v197 row_ror:1 row_mask:0xf bank_mask:0xf
	v_fmac_f32_dpp v34, v142, v212 row_ror:2 row_mask:0xf bank_mask:0xf
	v_fmac_f32_dpp v0, v143, v210 row_ror:2 row_mask:0xf bank_mask:0xf
	s_nop 0
	v_mov_b32_e32 v35, v0
	v_pk_fma_f32 v[0:1], v[142:143], v[42:43], v[162:163]
	v_pk_fma_f32 v[2:3], v[140:141], v[40:41], v[160:161]
	v_mov_b32_e32 v62, v0
	v_mov_b32_e32 v60, v2
	v_cndmask_b32_e64 v0, 0, 1, s[34:35]
	s_nop 1
	v_fmac_f32_dpp v60, v140, v148 row_shr:1 row_mask:0xf bank_mask:0xf bound_ctrl:1
	v_fmac_f32_dpp v3, v141, v149 row_shr:1 row_mask:0xf bank_mask:0xf bound_ctrl:1
	v_fmac_f32_dpp v60, v140, v152 row_shr:2 row_mask:0xf bank_mask:0xf bound_ctrl:1
	v_fmac_f32_dpp v3, v141, v153 row_shr:2 row_mask:0xf bank_mask:0xf bound_ctrl:1
	v_fmac_f32_dpp v62, v142, v150 row_shr:1 row_mask:0xf bank_mask:0xf bound_ctrl:1
	v_fmac_f32_dpp v1, v143, v151 row_shr:1 row_mask:0xf bank_mask:0xf bound_ctrl:1
	v_fmac_f32_dpp v62, v142, v154 row_shr:2 row_mask:0xf bank_mask:0xf bound_ctrl:1
	v_fmac_f32_dpp v1, v143, v155 row_shr:2 row_mask:0xf bank_mask:0xf bound_ctrl:1
	v_cmp_ne_u32_e64 s[12:13], 1, v0
	v_mov_b32_e32 v61, v3
	s_andn2_b64 vcc, exec, s[34:35]
	v_mov_b32_e32 v63, v1
	s_cbranch_vccnz .LBB0_1002
	ds_read_b128 v[8:11], v191
	ds_read_b128 v[140:143], v193
	s_waitcnt lgkmcnt(0)
	v_cndmask_b32_e64 v0, v8, v140, s[8:9]
	v_mul_f32_e32 v0, v211, v0
	v_fmac_f32_e32 v0, v195, v8
	v_add_f32_e32 v60, v60, v0
	v_cndmask_b32_e64 v0, v10, v142, s[8:9]
	v_mul_f32_e32 v0, v212, v0
	v_fmac_f32_e32 v0, v199, v10
	v_cndmask_b32_e64 v2, v9, v141, s[8:9]
	v_add_f32_e32 v62, v62, v0
	v_cndmask_b32_e64 v0, v11, v143, s[8:9]
	v_mul_f32_e32 v2, v213, v2
	v_mul_f32_e32 v0, v210, v0
	v_fmac_f32_e32 v2, v201, v9
	v_fmac_f32_e32 v0, v197, v11
	v_add_f32_e32 v61, v3, v2
	v_add_f32_e32 v63, v1, v0
.LBB0_1002:
	s_add_i32 s5, s5, s80
	s_add_i32 s14, s5, 0xfffffc00
	v_pk_fma_f32 v[2:3], v[22:23], v[42:43], v[162:163]
	v_pk_fma_f32 v[0:1], v[20:21], v[40:41], v[160:161]
	v_add_u32_e32 v156, s14, v189
	s_add_i32 s14, s5, 0xfffff800
	v_fmac_f32_dpp v0, v20, v148 row_shr:1 row_mask:0xf bank_mask:0xf bound_ctrl:1
	v_fmac_f32_dpp v1, v21, v149 row_shr:1 row_mask:0xf bank_mask:0xf bound_ctrl:1
	v_fmac_f32_dpp v0, v20, v152 row_shr:2 row_mask:0xf bank_mask:0xf bound_ctrl:1
	v_fmac_f32_dpp v1, v21, v153 row_shr:2 row_mask:0xf bank_mask:0xf bound_ctrl:1
	v_fmac_f32_dpp v2, v22, v150 row_shr:1 row_mask:0xf bank_mask:0xf bound_ctrl:1
	v_fmac_f32_dpp v3, v23, v151 row_shr:1 row_mask:0xf bank_mask:0xf bound_ctrl:1
	v_fmac_f32_dpp v2, v22, v154 row_shr:2 row_mask:0xf bank_mask:0xf bound_ctrl:1
	v_fmac_f32_dpp v3, v23, v155 row_shr:2 row_mask:0xf bank_mask:0xf bound_ctrl:1
	v_add_u32_e32 v157, s14, v189
	v_fmac_f32_dpp v0, v48, v195 row_ror:1 row_mask:0xf bank_mask:0xf
	v_fmac_f32_dpp v1, v49, v201 row_ror:1 row_mask:0xf bank_mask:0xf
	v_fmac_f32_dpp v0, v48, v211 row_ror:2 row_mask:0xf bank_mask:0xf
	v_fmac_f32_dpp v1, v49, v213 row_ror:2 row_mask:0xf bank_mask:0xf
	v_fmac_f32_dpp v2, v50, v199 row_ror:1 row_mask:0xf bank_mask:0xf
	v_fmac_f32_dpp v3, v51, v197 row_ror:1 row_mask:0xf bank_mask:0xf
	v_fmac_f32_dpp v2, v50, v212 row_ror:2 row_mask:0xf bank_mask:0xf
	v_fmac_f32_dpp v3, v51, v210 row_ror:2 row_mask:0xf bank_mask:0xf
	s_nop 0
	v_pk_fma_f32 v[10:11], v[50:51], v[42:43], v[162:163]
	v_pk_fma_f32 v[8:9], v[48:49], v[40:41], v[160:161]
	s_nop 0
	s_nop 1
	v_fmac_f32_dpp v8, v48, v148 row_shr:1 row_mask:0xf bank_mask:0xf bound_ctrl:1
	v_fmac_f32_dpp v9, v49, v149 row_shr:1 row_mask:0xf bank_mask:0xf bound_ctrl:1
	v_fmac_f32_dpp v8, v48, v152 row_shr:2 row_mask:0xf bank_mask:0xf bound_ctrl:1
	v_fmac_f32_dpp v9, v49, v153 row_shr:2 row_mask:0xf bank_mask:0xf bound_ctrl:1
	v_fmac_f32_dpp v10, v50, v150 row_shr:1 row_mask:0xf bank_mask:0xf bound_ctrl:1
	v_fmac_f32_dpp v11, v51, v151 row_shr:1 row_mask:0xf bank_mask:0xf bound_ctrl:1
	v_fmac_f32_dpp v10, v50, v154 row_shr:2 row_mask:0xf bank_mask:0xf bound_ctrl:1
	v_fmac_f32_dpp v11, v51, v155 row_shr:2 row_mask:0xf bank_mask:0xf bound_ctrl:1
	s_nop 0
	v_fmac_f32_dpp v8, v68, v195 row_ror:1 row_mask:0xf bank_mask:0xf
	v_fmac_f32_dpp v9, v69, v201 row_ror:1 row_mask:0xf bank_mask:0xf
	v_fmac_f32_dpp v8, v68, v211 row_ror:2 row_mask:0xf bank_mask:0xf
	v_fmac_f32_dpp v9, v69, v213 row_ror:2 row_mask:0xf bank_mask:0xf
	v_fmac_f32_dpp v10, v70, v199 row_ror:1 row_mask:0xf bank_mask:0xf
	v_fmac_f32_dpp v11, v71, v197 row_ror:1 row_mask:0xf bank_mask:0xf
	v_fmac_f32_dpp v10, v70, v212 row_ror:2 row_mask:0xf bank_mask:0xf
	v_fmac_f32_dpp v11, v71, v210 row_ror:2 row_mask:0xf bank_mask:0xf
	s_nop 0
	v_pk_fma_f32 v[22:23], v[70:71], v[42:43], v[162:163]
	v_pk_fma_f32 v[20:21], v[68:69], v[40:41], v[160:161]
	s_nop 0
	s_nop 1
	v_fmac_f32_dpp v20, v68, v148 row_shr:1 row_mask:0xf bank_mask:0xf bound_ctrl:1
	v_fmac_f32_dpp v21, v69, v149 row_shr:1 row_mask:0xf bank_mask:0xf bound_ctrl:1
	v_fmac_f32_dpp v20, v68, v152 row_shr:2 row_mask:0xf bank_mask:0xf bound_ctrl:1
	v_fmac_f32_dpp v21, v69, v153 row_shr:2 row_mask:0xf bank_mask:0xf bound_ctrl:1
	v_fmac_f32_dpp v22, v70, v150 row_shr:1 row_mask:0xf bank_mask:0xf bound_ctrl:1
	v_fmac_f32_dpp v23, v71, v151 row_shr:1 row_mask:0xf bank_mask:0xf bound_ctrl:1
	v_fmac_f32_dpp v22, v70, v154 row_shr:2 row_mask:0xf bank_mask:0xf bound_ctrl:1
	v_fmac_f32_dpp v23, v71, v155 row_shr:2 row_mask:0xf bank_mask:0xf bound_ctrl:1
	s_nop 0
	v_fmac_f32_dpp v20, v80, v195 row_ror:1 row_mask:0xf bank_mask:0xf
	v_fmac_f32_dpp v21, v81, v201 row_ror:1 row_mask:0xf bank_mask:0xf
	v_fmac_f32_dpp v20, v80, v211 row_ror:2 row_mask:0xf bank_mask:0xf
	v_fmac_f32_dpp v21, v81, v213 row_ror:2 row_mask:0xf bank_mask:0xf
	v_fmac_f32_dpp v22, v82, v199 row_ror:1 row_mask:0xf bank_mask:0xf
	v_fmac_f32_dpp v23, v83, v197 row_ror:1 row_mask:0xf bank_mask:0xf
	v_fmac_f32_dpp v22, v82, v212 row_ror:2 row_mask:0xf bank_mask:0xf
	v_fmac_f32_dpp v23, v83, v210 row_ror:2 row_mask:0xf bank_mask:0xf
	s_nop 0
	v_cndmask_b32_e64 v48, 0, 1, s[36:37]
	v_pk_fma_f32 v[42:43], v[82:83], v[42:43], v[162:163]
	v_pk_fma_f32 v[40:41], v[80:81], v[40:41], v[160:161]
	v_cmp_ne_u32_e64 s[14:15], 1, v48
	s_andn2_b64 vcc, exec, s[36:37]
	s_nop 1
	v_fmac_f32_dpp v40, v80, v148 row_shr:1 row_mask:0xf bank_mask:0xf bound_ctrl:1
	v_fmac_f32_dpp v41, v81, v149 row_shr:1 row_mask:0xf bank_mask:0xf bound_ctrl:1
	v_fmac_f32_dpp v40, v80, v152 row_shr:2 row_mask:0xf bank_mask:0xf bound_ctrl:1
	v_fmac_f32_dpp v41, v81, v153 row_shr:2 row_mask:0xf bank_mask:0xf bound_ctrl:1
	v_fmac_f32_dpp v42, v82, v150 row_shr:1 row_mask:0xf bank_mask:0xf bound_ctrl:1
	v_fmac_f32_dpp v43, v83, v151 row_shr:1 row_mask:0xf bank_mask:0xf bound_ctrl:1
	v_fmac_f32_dpp v42, v82, v154 row_shr:2 row_mask:0xf bank_mask:0xf bound_ctrl:1
	v_fmac_f32_dpp v43, v83, v155 row_shr:2 row_mask:0xf bank_mask:0xf bound_ctrl:1
	s_cbranch_vccnz .LBB0_1004
	ds_read_b128 v[48:51], v156
	ds_read_b128 v[68:71], v157
	s_waitcnt lgkmcnt(0)
	v_cndmask_b32_e64 v68, v48, v68, s[8:9]
	v_mul_f32_e32 v68, v211, v68
	v_fmac_f32_e32 v68, v195, v48
	v_cndmask_b32_e64 v48, v50, v70, s[8:9]
	v_mul_f32_e32 v48, v212, v48
	v_fmac_f32_e32 v48, v199, v50
	v_cndmask_b32_e64 v69, v49, v69, s[8:9]
	v_add_f32_e32 v42, v42, v48
	v_cndmask_b32_e64 v48, v51, v71, s[8:9]
	v_mul_f32_e32 v69, v213, v69
	v_mul_f32_e32 v48, v210, v48
	v_fmac_f32_e32 v69, v201, v49
	v_fmac_f32_e32 v48, v197, v51
	v_add_f32_e32 v40, v40, v68
	v_add_f32_e32 v41, v41, v69
	v_add_f32_e32 v43, v43, v48
.LBB0_1004:
	ds_read_b128 v[140:143], v187 offset:9232
	ds_read_b128 v[144:147], v187 offset:8208
	ds_read_b128 v[148:151], v187 offset:10256
	ds_read_b128 v[152:155], v187 offset:11280
	s_waitcnt lgkmcnt(3)
	v_cndmask_b32_e64 v159, 0, v140, s[8:9]
	s_waitcnt lgkmcnt(2)
	v_cndmask_b32_e64 v163, 0, v144, s[10:11]
	v_cndmask_b32_e64 v161, 0, v141, s[8:9]
	s_waitcnt lgkmcnt(0)
	v_pk_fma_f32 v[70:71], v[98:99], v[150:151], v[154:155]
	v_pk_fma_f32 v[68:69], v[96:97], v[148:149], v[152:153]
	v_cndmask_b32_e64 v165, 0, v145, s[10:11]
	s_nop 1
	v_fmac_f32_dpp v68, v96, v140 row_shr:1 row_mask:0xf bank_mask:0xf bound_ctrl:1
	v_fmac_f32_dpp v69, v97, v141 row_shr:1 row_mask:0xf bank_mask:0xf bound_ctrl:1
	v_fmac_f32_dpp v68, v96, v144 row_shr:2 row_mask:0xf bank_mask:0xf bound_ctrl:1
	v_fmac_f32_dpp v69, v97, v145 row_shr:2 row_mask:0xf bank_mask:0xf bound_ctrl:1
	v_fmac_f32_dpp v70, v98, v142 row_shr:1 row_mask:0xf bank_mask:0xf bound_ctrl:1
	v_fmac_f32_dpp v71, v99, v143 row_shr:1 row_mask:0xf bank_mask:0xf bound_ctrl:1
	v_fmac_f32_dpp v70, v98, v146 row_shr:2 row_mask:0xf bank_mask:0xf bound_ctrl:1
	v_fmac_f32_dpp v71, v99, v147 row_shr:2 row_mask:0xf bank_mask:0xf bound_ctrl:1
	v_cndmask_b32_e64 v160, 0, v142, s[8:9]
	v_cndmask_b32_e64 v164, 0, v146, s[10:11]
	v_cndmask_b32_e64 v158, 0, v143, s[8:9]
	v_cndmask_b32_e64 v162, 0, v147, s[10:11]
	v_fmac_f32_dpp v68, v136, v159 row_ror:1 row_mask:0xf bank_mask:0xf
	v_fmac_f32_dpp v69, v137, v161 row_ror:1 row_mask:0xf bank_mask:0xf
	v_fmac_f32_dpp v68, v136, v163 row_ror:2 row_mask:0xf bank_mask:0xf
	v_fmac_f32_dpp v69, v137, v165 row_ror:2 row_mask:0xf bank_mask:0xf
	v_fmac_f32_dpp v70, v138, v160 row_ror:1 row_mask:0xf bank_mask:0xf
	v_fmac_f32_dpp v71, v139, v158 row_ror:1 row_mask:0xf bank_mask:0xf
	v_fmac_f32_dpp v70, v138, v164 row_ror:2 row_mask:0xf bank_mask:0xf
	v_fmac_f32_dpp v71, v139, v162 row_ror:2 row_mask:0xf bank_mask:0xf
	s_nop 0
	v_pk_fma_f32 v[82:83], v[138:139], v[150:151], v[154:155]
	v_pk_fma_f32 v[80:81], v[136:137], v[148:149], v[152:153]
	v_mov_b32_e32 v49, v83
	v_mov_b32_e32 v48, v81
	s_nop 1
	v_fmac_f32_dpp v80, v136, v140 row_shr:1 row_mask:0xf bank_mask:0xf bound_ctrl:1
	v_fmac_f32_dpp v48, v137, v141 row_shr:1 row_mask:0xf bank_mask:0xf bound_ctrl:1
	v_fmac_f32_dpp v80, v136, v144 row_shr:2 row_mask:0xf bank_mask:0xf bound_ctrl:1
	v_fmac_f32_dpp v48, v137, v145 row_shr:2 row_mask:0xf bank_mask:0xf bound_ctrl:1
	v_fmac_f32_dpp v82, v138, v142 row_shr:1 row_mask:0xf bank_mask:0xf bound_ctrl:1
	v_fmac_f32_dpp v49, v139, v143 row_shr:1 row_mask:0xf bank_mask:0xf bound_ctrl:1
	v_fmac_f32_dpp v82, v138, v146 row_shr:2 row_mask:0xf bank_mask:0xf bound_ctrl:1
	v_fmac_f32_dpp v49, v139, v147 row_shr:2 row_mask:0xf bank_mask:0xf bound_ctrl:1
	s_nop 0
	v_fmac_f32_dpp v80, v120, v159 row_ror:1 row_mask:0xf bank_mask:0xf
	v_fmac_f32_dpp v48, v121, v161 row_ror:1 row_mask:0xf bank_mask:0xf
	v_fmac_f32_dpp v80, v120, v163 row_ror:2 row_mask:0xf bank_mask:0xf
	v_fmac_f32_dpp v48, v121, v165 row_ror:2 row_mask:0xf bank_mask:0xf
	v_fmac_f32_dpp v82, v122, v160 row_ror:1 row_mask:0xf bank_mask:0xf
	v_fmac_f32_dpp v49, v123, v158 row_ror:1 row_mask:0xf bank_mask:0xf
	v_fmac_f32_dpp v82, v122, v164 row_ror:2 row_mask:0xf bank_mask:0xf
	v_fmac_f32_dpp v49, v123, v162 row_ror:2 row_mask:0xf bank_mask:0xf
	s_nop 0
	v_mov_b32_e32 v81, v48
	v_mov_b32_e32 v83, v49
	v_pk_fma_f32 v[98:99], v[122:123], v[150:151], v[154:155]
	v_pk_fma_f32 v[96:97], v[120:121], v[148:149], v[152:153]
	v_mov_b32_e32 v48, v99
	s_nop 1
	v_fmac_f32_dpp v96, v120, v140 row_shr:1 row_mask:0xf bank_mask:0xf bound_ctrl:1
	v_fmac_f32_dpp v97, v121, v141 row_shr:1 row_mask:0xf bank_mask:0xf bound_ctrl:1
	v_fmac_f32_dpp v96, v120, v144 row_shr:2 row_mask:0xf bank_mask:0xf bound_ctrl:1
	v_fmac_f32_dpp v97, v121, v145 row_shr:2 row_mask:0xf bank_mask:0xf bound_ctrl:1
	v_fmac_f32_dpp v98, v122, v142 row_shr:1 row_mask:0xf bank_mask:0xf bound_ctrl:1
	v_fmac_f32_dpp v48, v123, v143 row_shr:1 row_mask:0xf bank_mask:0xf bound_ctrl:1
	v_fmac_f32_dpp v98, v122, v146 row_shr:2 row_mask:0xf bank_mask:0xf bound_ctrl:1
	v_fmac_f32_dpp v48, v123, v147 row_shr:2 row_mask:0xf bank_mask:0xf bound_ctrl:1
	s_nop 0
	v_fmac_f32_dpp v96, v132, v159 row_ror:1 row_mask:0xf bank_mask:0xf
	v_fmac_f32_dpp v97, v133, v161 row_ror:1 row_mask:0xf bank_mask:0xf
	v_fmac_f32_dpp v96, v132, v163 row_ror:2 row_mask:0xf bank_mask:0xf
	v_fmac_f32_dpp v97, v133, v165 row_ror:2 row_mask:0xf bank_mask:0xf
	v_fmac_f32_dpp v98, v134, v160 row_ror:1 row_mask:0xf bank_mask:0xf
	v_fmac_f32_dpp v48, v135, v158 row_ror:1 row_mask:0xf bank_mask:0xf
	v_fmac_f32_dpp v98, v134, v164 row_ror:2 row_mask:0xf bank_mask:0xf
	v_fmac_f32_dpp v48, v135, v162 row_ror:2 row_mask:0xf bank_mask:0xf
	s_nop 0
	v_mov_b32_e32 v99, v48
	v_pk_fma_f32 v[48:49], v[134:135], v[150:151], v[154:155]
	v_pk_fma_f32 v[50:51], v[132:133], v[148:149], v[152:153]
	v_mov_b32_e32 v122, v48
	v_mov_b32_e32 v120, v50
	s_nop 1
	v_fmac_f32_dpp v120, v132, v140 row_shr:1 row_mask:0xf bank_mask:0xf bound_ctrl:1
	v_fmac_f32_dpp v51, v133, v141 row_shr:1 row_mask:0xf bank_mask:0xf bound_ctrl:1
	v_fmac_f32_dpp v120, v132, v144 row_shr:2 row_mask:0xf bank_mask:0xf bound_ctrl:1
	v_fmac_f32_dpp v51, v133, v145 row_shr:2 row_mask:0xf bank_mask:0xf bound_ctrl:1
	v_fmac_f32_dpp v122, v134, v142 row_shr:1 row_mask:0xf bank_mask:0xf bound_ctrl:1
	v_fmac_f32_dpp v49, v135, v143 row_shr:1 row_mask:0xf bank_mask:0xf bound_ctrl:1
	v_fmac_f32_dpp v122, v134, v146 row_shr:2 row_mask:0xf bank_mask:0xf bound_ctrl:1
	v_fmac_f32_dpp v49, v135, v147 row_shr:2 row_mask:0xf bank_mask:0xf bound_ctrl:1
	s_and_b64 vcc, exec, s[12:13]
	v_mov_b32_e32 v121, v51
	v_mov_b32_e32 v123, v49
	s_cbranch_vccnz .LBB0_1006
	ds_read_b128 v[132:135], v191 offset:16
	ds_read_b128 v[136:139], v193 offset:16
	s_waitcnt lgkmcnt(0)
	v_cndmask_b32_e64 v48, v132, v136, s[8:9]
	v_mul_f32_e32 v48, v163, v48
	v_fmac_f32_e32 v48, v159, v132
	v_add_f32_e32 v120, v120, v48
	v_cndmask_b32_e64 v48, v134, v138, s[8:9]
	v_mul_f32_e32 v48, v164, v48
	v_fmac_f32_e32 v48, v160, v134
	v_cndmask_b32_e64 v50, v133, v137, s[8:9]
	v_add_f32_e32 v122, v122, v48
	v_cndmask_b32_e64 v48, v135, v139, s[8:9]
	v_mul_f32_e32 v50, v165, v50
	v_mul_f32_e32 v48, v162, v48
	v_fmac_f32_e32 v50, v161, v133
	v_fmac_f32_e32 v48, v158, v135
	v_add_f32_e32 v121, v51, v50
	v_add_f32_e32 v123, v49, v48

.LBB0_1008:
	ds_read_b128 v[136:139], v187 offset:9728
	ds_read_b128 v[140:143], v187 offset:8704
	ds_read_b128 v[144:147], v187 offset:10752
	ds_read_b128 v[148:151], v187 offset:11776
	s_add_i32 s46, s4, 0xfffffe00
	s_addk_i32 s4, 0xfa00
	s_waitcnt lgkmcnt(3)
	v_cndmask_b32_e64 v157, 0, v136, s[8:9]
	s_waitcnt lgkmcnt(2)
	v_cndmask_b32_e64 v161, 0, v140, s[10:11]
	s_waitcnt lgkmcnt(0)
	v_pk_fma_f32 v[130:131], v[126:127], v[146:147], v[150:151]
	v_pk_fma_f32 v[128:129], v[124:125], v[144:145], v[148:149]
	v_cndmask_b32_e64 v159, 0, v137, s[8:9]
	s_nop 1
	v_fmac_f32_dpp v128, v124, v136 row_shr:1 row_mask:0xf bank_mask:0xf bound_ctrl:1
	v_fmac_f32_dpp v129, v125, v137 row_shr:1 row_mask:0xf bank_mask:0xf bound_ctrl:1
	v_fmac_f32_dpp v128, v124, v140 row_shr:2 row_mask:0xf bank_mask:0xf bound_ctrl:1
	v_fmac_f32_dpp v129, v125, v141 row_shr:2 row_mask:0xf bank_mask:0xf bound_ctrl:1
	v_fmac_f32_dpp v130, v126, v138 row_shr:1 row_mask:0xf bank_mask:0xf bound_ctrl:1
	v_fmac_f32_dpp v131, v127, v139 row_shr:1 row_mask:0xf bank_mask:0xf bound_ctrl:1
	v_fmac_f32_dpp v130, v126, v142 row_shr:2 row_mask:0xf bank_mask:0xf bound_ctrl:1
	v_fmac_f32_dpp v131, v127, v143 row_shr:2 row_mask:0xf bank_mask:0xf bound_ctrl:1
	v_cndmask_b32_e64 v163, 0, v141, s[10:11]
	v_cndmask_b32_e64 v158, 0, v138, s[8:9]
	v_cndmask_b32_e64 v162, 0, v142, s[10:11]
	v_cndmask_b32_e64 v156, 0, v139, s[8:9]
	v_cndmask_b32_e64 v160, 0, v143, s[10:11]
	v_add_u32_e32 v154, s46, v189
	v_add_u32_e32 v155, s4, v189
	v_fmac_f32_dpp v128, v112, v157 row_ror:1 row_mask:0xf bank_mask:0xf
	v_fmac_f32_dpp v129, v113, v159 row_ror:1 row_mask:0xf bank_mask:0xf
	v_fmac_f32_dpp v128, v112, v161 row_ror:2 row_mask:0xf bank_mask:0xf
	v_fmac_f32_dpp v129, v113, v163 row_ror:2 row_mask:0xf bank_mask:0xf
	v_fmac_f32_dpp v130, v114, v158 row_ror:1 row_mask:0xf bank_mask:0xf
	v_fmac_f32_dpp v131, v115, v156 row_ror:1 row_mask:0xf bank_mask:0xf
	v_fmac_f32_dpp v130, v114, v162 row_ror:2 row_mask:0xf bank_mask:0xf
	v_fmac_f32_dpp v131, v115, v160 row_ror:2 row_mask:0xf bank_mask:0xf
	s_nop 0
	v_pk_fma_f32 v[126:127], v[114:115], v[146:147], v[150:151]
	v_pk_fma_f32 v[124:125], v[112:113], v[144:145], v[148:149]
	s_nop 0
	s_nop 1
	v_fmac_f32_dpp v124, v112, v136 row_shr:1 row_mask:0xf bank_mask:0xf bound_ctrl:1
	v_fmac_f32_dpp v125, v113, v137 row_shr:1 row_mask:0xf bank_mask:0xf bound_ctrl:1
	v_fmac_f32_dpp v124, v112, v140 row_shr:2 row_mask:0xf bank_mask:0xf bound_ctrl:1
	v_fmac_f32_dpp v125, v113, v141 row_shr:2 row_mask:0xf bank_mask:0xf bound_ctrl:1
	v_mov_b32_e32 v112, v127
	s_nop 1
	v_fmac_f32_dpp v126, v114, v138 row_shr:1 row_mask:0xf bank_mask:0xf bound_ctrl:1
	v_fmac_f32_dpp v112, v115, v139 row_shr:1 row_mask:0xf bank_mask:0xf bound_ctrl:1
	v_fmac_f32_dpp v126, v114, v142 row_shr:2 row_mask:0xf bank_mask:0xf bound_ctrl:1
	v_fmac_f32_dpp v112, v115, v143 row_shr:2 row_mask:0xf bank_mask:0xf bound_ctrl:1
	v_fmac_f32_dpp v124, v100, v157 row_ror:1 row_mask:0xf bank_mask:0xf
	v_fmac_f32_dpp v125, v101, v159 row_ror:1 row_mask:0xf bank_mask:0xf
	v_fmac_f32_dpp v124, v100, v161 row_ror:2 row_mask:0xf bank_mask:0xf
	v_fmac_f32_dpp v125, v101, v163 row_ror:2 row_mask:0xf bank_mask:0xf
	s_nop 0
	v_fmac_f32_dpp v126, v102, v158 row_ror:1 row_mask:0xf bank_mask:0xf
	v_fmac_f32_dpp v112, v103, v156 row_ror:1 row_mask:0xf bank_mask:0xf
	v_fmac_f32_dpp v126, v102, v162 row_ror:2 row_mask:0xf bank_mask:0xf
	v_fmac_f32_dpp v112, v103, v160 row_ror:2 row_mask:0xf bank_mask:0xf
	s_nop 0
	v_mov_b32_e32 v127, v112
	v_pk_fma_f32 v[114:115], v[102:103], v[146:147], v[150:151]
	v_pk_fma_f32 v[112:113], v[100:101], v[144:145], v[148:149]
	s_nop 0
	s_nop 1
	v_fmac_f32_dpp v112, v100, v136 row_shr:1 row_mask:0xf bank_mask:0xf bound_ctrl:1
	v_fmac_f32_dpp v113, v101, v137 row_shr:1 row_mask:0xf bank_mask:0xf bound_ctrl:1
	v_fmac_f32_dpp v112, v100, v140 row_shr:2 row_mask:0xf bank_mask:0xf bound_ctrl:1
	v_fmac_f32_dpp v113, v101, v141 row_shr:2 row_mask:0xf bank_mask:0xf bound_ctrl:1
	v_mov_b32_e32 v100, v115
	s_nop 1
	v_fmac_f32_dpp v114, v102, v138 row_shr:1 row_mask:0xf bank_mask:0xf bound_ctrl:1
	v_fmac_f32_dpp v100, v103, v139 row_shr:1 row_mask:0xf bank_mask:0xf bound_ctrl:1
	v_fmac_f32_dpp v114, v102, v142 row_shr:2 row_mask:0xf bank_mask:0xf bound_ctrl:1
	v_fmac_f32_dpp v100, v103, v143 row_shr:2 row_mask:0xf bank_mask:0xf bound_ctrl:1
	v_fmac_f32_dpp v112, v88, v157 row_ror:1 row_mask:0xf bank_mask:0xf
	v_fmac_f32_dpp v113, v89, v159 row_ror:1 row_mask:0xf bank_mask:0xf
	v_fmac_f32_dpp v112, v88, v161 row_ror:2 row_mask:0xf bank_mask:0xf
	v_fmac_f32_dpp v113, v89, v163 row_ror:2 row_mask:0xf bank_mask:0xf
	s_nop 0
	v_fmac_f32_dpp v114, v90, v158 row_ror:1 row_mask:0xf bank_mask:0xf
	v_fmac_f32_dpp v100, v91, v156 row_ror:1 row_mask:0xf bank_mask:0xf
	v_fmac_f32_dpp v114, v90, v162 row_ror:2 row_mask:0xf bank_mask:0xf
	v_fmac_f32_dpp v100, v91, v160 row_ror:2 row_mask:0xf bank_mask:0xf
	s_nop 0
	v_mov_b32_e32 v115, v100
	v_pk_fma_f32 v[100:101], v[90:91], v[146:147], v[150:151]
	v_pk_fma_f32 v[102:103], v[88:89], v[144:145], v[148:149]
	v_mov_b32_e32 v134, v100
	v_mov_b32_e32 v132, v102
	s_nop 1
	v_fmac_f32_dpp v132, v88, v136 row_shr:1 row_mask:0xf bank_mask:0xf bound_ctrl:1
	v_fmac_f32_dpp v103, v89, v137 row_shr:1 row_mask:0xf bank_mask:0xf bound_ctrl:1
	v_fmac_f32_dpp v132, v88, v140 row_shr:2 row_mask:0xf bank_mask:0xf bound_ctrl:1
	v_fmac_f32_dpp v103, v89, v141 row_shr:2 row_mask:0xf bank_mask:0xf bound_ctrl:1
	v_fmac_f32_dpp v134, v90, v138 row_shr:1 row_mask:0xf bank_mask:0xf bound_ctrl:1
	v_fmac_f32_dpp v101, v91, v139 row_shr:1 row_mask:0xf bank_mask:0xf bound_ctrl:1
	v_fmac_f32_dpp v134, v90, v142 row_shr:2 row_mask:0xf bank_mask:0xf bound_ctrl:1
	v_fmac_f32_dpp v101, v91, v143 row_shr:2 row_mask:0xf bank_mask:0xf bound_ctrl:1
	s_and_b64 vcc, exec, s[12:13]
	v_mov_b32_e32 v133, v103
	v_mov_b32_e32 v135, v101
	s_cbranch_vccnz .LBB0_1010
	ds_read_b128 v[88:91], v154
	ds_read_b128 v[164:167], v155
	s_waitcnt lgkmcnt(0)
	v_cndmask_b32_e64 v100, v88, v164, s[8:9]
	v_mul_f32_e32 v100, v161, v100
	v_fmac_f32_e32 v100, v157, v88
	v_cndmask_b32_e64 v88, v90, v166, s[8:9]
	v_mul_f32_e32 v88, v162, v88
	v_fmac_f32_e32 v88, v158, v90
	v_cndmask_b32_e64 v102, v89, v165, s[8:9]
	v_add_f32_e32 v134, v134, v88
	v_cndmask_b32_e64 v88, v91, v167, s[8:9]
	v_mul_f32_e32 v102, v163, v102
	v_mul_f32_e32 v88, v160, v88
	v_fmac_f32_e32 v102, v159, v89
	v_fmac_f32_e32 v88, v156, v91
	v_add_f32_e32 v132, v132, v100
	v_add_f32_e32 v133, v103, v102
	v_add_f32_e32 v135, v101, v88

.LBB0_1015:
	v_pk_fma_f32 v[26:27], v[58:59], v[142:143], v[146:147]
	v_pk_fma_f32 v[24:25], v[56:57], v[140:141], v[144:145]
	s_nop 0
	s_nop 1
	v_fmac_f32_dpp v24, v56, v116 row_shr:1 row_mask:0xf bank_mask:0xf bound_ctrl:1
	v_fmac_f32_dpp v25, v57, v117 row_shr:1 row_mask:0xf bank_mask:0xf bound_ctrl:1
	v_fmac_f32_dpp v24, v56, v136 row_shr:2 row_mask:0xf bank_mask:0xf bound_ctrl:1
	v_fmac_f32_dpp v25, v57, v137 row_shr:2 row_mask:0xf bank_mask:0xf bound_ctrl:1
	v_fmac_f32_dpp v26, v58, v118 row_shr:1 row_mask:0xf bank_mask:0xf bound_ctrl:1
	v_fmac_f32_dpp v27, v59, v119 row_shr:1 row_mask:0xf bank_mask:0xf bound_ctrl:1
	v_fmac_f32_dpp v26, v58, v138 row_shr:2 row_mask:0xf bank_mask:0xf bound_ctrl:1
	v_fmac_f32_dpp v27, v59, v139 row_shr:2 row_mask:0xf bank_mask:0xf bound_ctrl:1
	s_nop 0
	v_fmac_f32_dpp v24, v44, v157 row_ror:1 row_mask:0xf bank_mask:0xf
	v_fmac_f32_dpp v25, v45, v159 row_ror:1 row_mask:0xf bank_mask:0xf
	v_fmac_f32_dpp v24, v44, v161 row_ror:2 row_mask:0xf bank_mask:0xf
	v_fmac_f32_dpp v25, v45, v163 row_ror:2 row_mask:0xf bank_mask:0xf
	v_fmac_f32_dpp v26, v46, v158 row_ror:1 row_mask:0xf bank_mask:0xf
	v_fmac_f32_dpp v27, v47, v156 row_ror:1 row_mask:0xf bank_mask:0xf
	v_fmac_f32_dpp v26, v46, v162 row_ror:2 row_mask:0xf bank_mask:0xf
	v_fmac_f32_dpp v27, v47, v160 row_ror:2 row_mask:0xf bank_mask:0xf
	s_nop 0
	v_pk_fma_f32 v[38:39], v[46:47], v[142:143], v[146:147]
	v_pk_fma_f32 v[36:37], v[44:45], v[140:141], v[144:145]
	s_nop 0
	s_nop 1
	v_fmac_f32_dpp v36, v44, v116 row_shr:1 row_mask:0xf bank_mask:0xf bound_ctrl:1
	v_fmac_f32_dpp v37, v45, v117 row_shr:1 row_mask:0xf bank_mask:0xf bound_ctrl:1
	v_fmac_f32_dpp v36, v44, v136 row_shr:2 row_mask:0xf bank_mask:0xf bound_ctrl:1
	v_fmac_f32_dpp v37, v45, v137 row_shr:2 row_mask:0xf bank_mask:0xf bound_ctrl:1
	v_fmac_f32_dpp v38, v46, v118 row_shr:1 row_mask:0xf bank_mask:0xf bound_ctrl:1
	v_fmac_f32_dpp v39, v47, v119 row_shr:1 row_mask:0xf bank_mask:0xf bound_ctrl:1
	v_fmac_f32_dpp v38, v46, v138 row_shr:2 row_mask:0xf bank_mask:0xf bound_ctrl:1
	v_fmac_f32_dpp v39, v47, v139 row_shr:2 row_mask:0xf bank_mask:0xf bound_ctrl:1
	s_nop 0
	v_fmac_f32_dpp v36, v28, v157 row_ror:1 row_mask:0xf bank_mask:0xf
	v_fmac_f32_dpp v37, v29, v159 row_ror:1 row_mask:0xf bank_mask:0xf
	v_fmac_f32_dpp v36, v28, v161 row_ror:2 row_mask:0xf bank_mask:0xf
	v_fmac_f32_dpp v37, v29, v163 row_ror:2 row_mask:0xf bank_mask:0xf
	v_fmac_f32_dpp v38, v30, v158 row_ror:1 row_mask:0xf bank_mask:0xf
	v_fmac_f32_dpp v39, v31, v156 row_ror:1 row_mask:0xf bank_mask:0xf
	v_fmac_f32_dpp v38, v30, v162 row_ror:2 row_mask:0xf bank_mask:0xf
	v_fmac_f32_dpp v39, v31, v160 row_ror:2 row_mask:0xf bank_mask:0xf
	s_nop 0
	v_pk_fma_f32 v[46:47], v[30:31], v[142:143], v[146:147]
	v_pk_fma_f32 v[44:45], v[28:29], v[140:141], v[144:145]
	s_nop 0
	s_nop 1
	v_fmac_f32_dpp v44, v28, v116 row_shr:1 row_mask:0xf bank_mask:0xf bound_ctrl:1
	v_fmac_f32_dpp v45, v29, v117 row_shr:1 row_mask:0xf bank_mask:0xf bound_ctrl:1
	v_fmac_f32_dpp v44, v28, v136 row_shr:2 row_mask:0xf bank_mask:0xf bound_ctrl:1
	v_fmac_f32_dpp v45, v29, v137 row_shr:2 row_mask:0xf bank_mask:0xf bound_ctrl:1
	v_mov_b32_e32 v28, v47
	s_nop 1
	v_fmac_f32_dpp v46, v30, v118 row_shr:1 row_mask:0xf bank_mask:0xf bound_ctrl:1
	v_fmac_f32_dpp v28, v31, v119 row_shr:1 row_mask:0xf bank_mask:0xf bound_ctrl:1
	v_fmac_f32_dpp v46, v30, v138 row_shr:2 row_mask:0xf bank_mask:0xf bound_ctrl:1
	v_fmac_f32_dpp v28, v31, v139 row_shr:2 row_mask:0xf bank_mask:0xf bound_ctrl:1
	v_fmac_f32_dpp v44, v12, v157 row_ror:1 row_mask:0xf bank_mask:0xf
	v_fmac_f32_dpp v45, v13, v159 row_ror:1 row_mask:0xf bank_mask:0xf
	v_fmac_f32_dpp v44, v12, v161 row_ror:2 row_mask:0xf bank_mask:0xf
	v_fmac_f32_dpp v45, v13, v163 row_ror:2 row_mask:0xf bank_mask:0xf
	s_nop 0
	v_fmac_f32_dpp v46, v14, v158 row_ror:1 row_mask:0xf bank_mask:0xf
	v_fmac_f32_dpp v28, v15, v156 row_ror:1 row_mask:0xf bank_mask:0xf
	v_fmac_f32_dpp v46, v14, v162 row_ror:2 row_mask:0xf bank_mask:0xf
	v_fmac_f32_dpp v28, v15, v160 row_ror:2 row_mask:0xf bank_mask:0xf
	s_nop 0
	v_mov_b32_e32 v47, v28
	v_pk_fma_f32 v[30:31], v[14:15], v[142:143], v[146:147]
	v_pk_fma_f32 v[28:29], v[12:13], v[140:141], v[144:145]
	s_and_b64 vcc, exec, s[14:15]
	s_nop 1
	v_fmac_f32_dpp v28, v12, v116 row_shr:1 row_mask:0xf bank_mask:0xf bound_ctrl:1
	v_fmac_f32_dpp v29, v13, v117 row_shr:1 row_mask:0xf bank_mask:0xf bound_ctrl:1
	v_fmac_f32_dpp v28, v12, v136 row_shr:2 row_mask:0xf bank_mask:0xf bound_ctrl:1
	v_fmac_f32_dpp v29, v13, v137 row_shr:2 row_mask:0xf bank_mask:0xf bound_ctrl:1
	v_fmac_f32_dpp v30, v14, v118 row_shr:1 row_mask:0xf bank_mask:0xf bound_ctrl:1
	v_fmac_f32_dpp v31, v15, v119 row_shr:1 row_mask:0xf bank_mask:0xf bound_ctrl:1
	v_fmac_f32_dpp v30, v14, v138 row_shr:2 row_mask:0xf bank_mask:0xf bound_ctrl:1
	v_fmac_f32_dpp v31, v15, v139 row_shr:2 row_mask:0xf bank_mask:0xf bound_ctrl:1
	s_cbranch_vccnz .LBB0_1017
	ds_read_b128 v[12:15], v152 offset:16
	ds_read_b128 v[56:59], v153 offset:16
	s_waitcnt lgkmcnt(0)
	v_cndmask_b32_e64 v56, v12, v56, s[8:9]
	v_mul_f32_e32 v56, v161, v56
	v_fmac_f32_e32 v56, v157, v12
	v_cndmask_b32_e64 v12, v14, v58, s[8:9]
	v_mul_f32_e32 v12, v162, v12
	v_fmac_f32_e32 v12, v158, v14
	v_cndmask_b32_e64 v57, v13, v57, s[8:9]
	v_add_f32_e32 v30, v30, v12
	v_cndmask_b32_e64 v12, v15, v59, s[8:9]
	v_mul_f32_e32 v57, v163, v57
	v_mul_f32_e32 v12, v160, v12
	v_fmac_f32_e32 v57, v159, v13
	v_fmac_f32_e32 v12, v156, v15
	v_add_f32_e32 v28, v28, v56
	v_add_f32_e32 v29, v29, v57
	v_add_f32_e32 v31, v31, v12
